# gemm160 loops: asymmetric LDS-DMA issue (waves 0-3 after their last MFMA, waves 4-7 right after the barrier) so SIMD partners do not stall on DMA issue together
# speedup vs baseline: 1.0215x; 1.0053x over previous
.Lg160i_pskip:
	s_or_b64 exec, exec, s[100:101]
	s_mov_b64 s[12:13], 0x80
	v_lshl_add_u64 v[192:193], v[90:91], 0, s[12:13]
	s_add_u32 m0, s98, 0x5000
	s_nop 0
	global_load_lds_dwordx4 v[192:193], off
	s_mov_b64 s[12:13], 0x20080
	v_lshl_add_u64 v[192:193], v[90:91], 0, s[12:13]
	s_add_u32 m0, s98, 0x7000
	s_nop 0
	global_load_lds_dwordx4 v[192:193], off
	s_mov_b64 s[12:13], 0x40080
	v_lshl_add_u64 v[192:193], v[90:91], 0, s[12:13]
	s_add_u32 m0, s98, 0x9000
	s_nop 0
	global_load_lds_dwordx4 v[192:193], off
	s_mov_b64 s[12:13], 0x60080
	v_lshl_add_u64 v[192:193], v[90:91], 0, s[12:13]
	s_add_u32 m0, s98, 0xb000
	s_nop 0
	global_load_lds_dwordx4 v[192:193], off
	s_cmp_eq_u64 s[4:5], 0
	s_cbranch_scc1 .Lg160i_q
.Lg160i_p:
	v_add_u32_e32 v168, s7, v95
	v_add_u32_e32 v169, s7, v97
	v_add_u32_e32 v196, v168, v99
	v_add_u32_e32 v200, v169, v99
	v_add_u32_e32 v168, v168, v98
	v_add_u32_e32 v169, v169, v98
	s_waitcnt vmcnt(7) lgkmcnt(0)
	s_barrier
	ds_read_b128 v[156:159], v168 offset:20480
	ds_read_b128 v[160:163], v168 offset:22528
	ds_read_b128 v[112:115], v169
	ds_read_b128 v[116:119], v169 offset:2048
	ds_read_b128 v[120:123], v169 offset:4096
	ds_read_b128 v[124:127], v169 offset:6144
	ds_read_b128 v[132:135], v169 offset:8192
	ds_read_b128 v[136:139], v169 offset:10240
	ds_read_b128 v[140:143], v169 offset:12288
	ds_read_b128 v[144:147], v169 offset:14336
	ds_read_b128 v[148:151], v169 offset:16384
	ds_read_b128 v[152:155], v169 offset:18432
	s_waitcnt lgkmcnt(9)
	v_mfma_f32_16x16x32_bf16 v[76:79], v[156:159], v[112:115], v[76:79]
	v_mfma_f32_16x16x32_bf16 v[72:75], v[160:163], v[112:115], v[72:75]
	ds_read_b128 v[204:207], v196 offset:20480
	s_waitcnt lgkmcnt(9)
	v_mfma_f32_16x16x32_bf16 v[68:71], v[156:159], v[116:119], v[68:71]
	v_mfma_f32_16x16x32_bf16 v[64:67], v[160:163], v[116:119], v[64:67]
	ds_read_b128 v[208:211], v196 offset:22528
	s_waitcnt lgkmcnt(9)
	v_mfma_f32_16x16x32_bf16 v[60:63], v[156:159], v[120:123], v[60:63]
	v_mfma_f32_16x16x32_bf16 v[56:59], v[160:163], v[120:123], v[56:59]
	ds_read_b128 v[164:167], v200
	s_waitcnt lgkmcnt(9)
	v_mfma_f32_16x16x32_bf16 v[52:55], v[156:159], v[124:127], v[52:55]
	v_mfma_f32_16x16x32_bf16 v[48:51], v[160:163], v[124:127], v[48:51]
	ds_read_b128 v[168:171], v200 offset:2048
	s_waitcnt lgkmcnt(9)
	v_mfma_f32_16x16x32_bf16 v[44:47], v[156:159], v[132:135], v[44:47]
	v_mfma_f32_16x16x32_bf16 v[40:43], v[160:163], v[132:135], v[40:43]
	ds_read_b128 v[172:175], v200 offset:4096
	s_waitcnt lgkmcnt(9)
	v_mfma_f32_16x16x32_bf16 v[36:39], v[156:159], v[136:139], v[36:39]
	v_mfma_f32_16x16x32_bf16 v[32:35], v[160:163], v[136:139], v[32:35]
	ds_read_b128 v[176:179], v200 offset:6144
	s_waitcnt lgkmcnt(9)
	v_mfma_f32_16x16x32_bf16 v[28:31], v[156:159], v[140:143], v[28:31]
	v_mfma_f32_16x16x32_bf16 v[24:27], v[160:163], v[140:143], v[24:27]
	ds_read_b128 v[180:183], v200 offset:8192
	s_waitcnt lgkmcnt(9)
	v_mfma_f32_16x16x32_bf16 v[20:23], v[156:159], v[144:147], v[20:23]
	v_mfma_f32_16x16x32_bf16 v[16:19], v[160:163], v[144:147], v[16:19]
	ds_read_b128 v[184:187], v200 offset:10240
	s_waitcnt lgkmcnt(9)
	v_mfma_f32_16x16x32_bf16 v[12:15], v[156:159], v[148:151], v[12:15]
	v_mfma_f32_16x16x32_bf16 v[8:11], v[160:163], v[148:151], v[8:11]
	ds_read_b128 v[188:191], v200 offset:12288
	s_waitcnt lgkmcnt(9)
	v_mfma_f32_16x16x32_bf16 v[4:7], v[156:159], v[152:155], v[4:7]
	v_mfma_f32_16x16x32_bf16 v[0:3], v[160:163], v[152:155], v[0:3]
	ds_read_b128 v[192:195], v200 offset:14336
	ds_read_b128 v[196:199], v200 offset:16384
	ds_read_b128 v[200:203], v200 offset:18432
	s_waitcnt lgkmcnt(9)
	v_mfma_f32_16x16x32_bf16 v[76:79], v[204:207], v[164:167], v[76:79]
	v_mfma_f32_16x16x32_bf16 v[72:75], v[208:211], v[164:167], v[72:75]
	s_waitcnt lgkmcnt(8)
	v_mfma_f32_16x16x32_bf16 v[68:71], v[204:207], v[168:171], v[68:71]
	v_mfma_f32_16x16x32_bf16 v[64:67], v[208:211], v[168:171], v[64:67]
	s_waitcnt lgkmcnt(7)
	v_mfma_f32_16x16x32_bf16 v[60:63], v[204:207], v[172:175], v[60:63]
	v_mfma_f32_16x16x32_bf16 v[56:59], v[208:211], v[172:175], v[56:59]
	s_waitcnt lgkmcnt(6)
	v_mfma_f32_16x16x32_bf16 v[52:55], v[204:207], v[176:179], v[52:55]
	v_mfma_f32_16x16x32_bf16 v[48:51], v[208:211], v[176:179], v[48:51]
	s_waitcnt lgkmcnt(5)
	v_mfma_f32_16x16x32_bf16 v[44:47], v[204:207], v[180:183], v[44:47]
	v_mfma_f32_16x16x32_bf16 v[40:43], v[208:211], v[180:183], v[40:43]
	s_waitcnt lgkmcnt(4)
	v_mfma_f32_16x16x32_bf16 v[36:39], v[204:207], v[184:187], v[36:39]
	v_mfma_f32_16x16x32_bf16 v[32:35], v[208:211], v[184:187], v[32:35]
	s_waitcnt lgkmcnt(3)
	v_mfma_f32_16x16x32_bf16 v[28:31], v[204:207], v[188:191], v[28:31]
	v_mfma_f32_16x16x32_bf16 v[24:27], v[208:211], v[188:191], v[24:27]
	s_waitcnt lgkmcnt(2)
	v_mfma_f32_16x16x32_bf16 v[20:23], v[204:207], v[192:195], v[20:23]
	v_mfma_f32_16x16x32_bf16 v[16:19], v[208:211], v[192:195], v[16:19]
	s_waitcnt lgkmcnt(1)
	v_mfma_f32_16x16x32_bf16 v[12:15], v[204:207], v[196:199], v[12:15]
	v_mfma_f32_16x16x32_bf16 v[8:11], v[208:211], v[196:199], v[8:11]
	s_waitcnt lgkmcnt(0)
	v_mfma_f32_16x16x32_bf16 v[4:7], v[204:207], v[200:203], v[4:7]
	v_mfma_f32_16x16x32_bf16 v[0:3], v[208:211], v[200:203], v[0:3]
	s_add_u32 s12, s7, 0x1a000
	s_cmp_ge_u32 s12, 0x27000
	s_cselect_b32 s13, 0x27000, 0
	s_sub_u32 s12, s12, s13
	v_add_u32_e32 v172, s12, v96
	s_add_u32 s12, s10, 0x80
	s_addc_u32 s13, s11, 0
	v_lshl_add_u64 v[92:93], v[88:89], 0, s[12:13]
	v_lshl_add_u64 v[190:191], v[90:91], 0, s[12:13]
	v_readfirstlane_b32 s98, v172
	v_lshl_add_u64 v[192:193], v[92:93], 0, s[78:79]
	s_mov_b32 m0, s98
	s_nop 0
	global_load_lds_dwordx4 v[192:193], off
	v_lshl_add_u64 v[192:193], v[92:93], 0, s[80:81]
	s_add_u32 m0, s98, 0x2000
	s_nop 0
	global_load_lds_dwordx4 v[192:193], off
	v_lshl_add_u64 v[192:193], v[92:93], 0, s[82:83]
	s_add_u32 m0, s98, 0x4000
	s_nop 0
	global_load_lds_dwordx4 v[192:193], off
	s_mov_b64 s[12:13], 0x80
	v_lshl_add_u64 v[192:193], v[190:191], 0, s[12:13]
	s_add_u32 m0, s98, 0x5000
	s_nop 0
	global_load_lds_dwordx4 v[192:193], off
	s_mov_b64 s[12:13], 0x20080
	v_lshl_add_u64 v[192:193], v[190:191], 0, s[12:13]
	s_add_u32 m0, s98, 0x7000
	s_nop 0
	global_load_lds_dwordx4 v[192:193], off
	s_mov_b64 s[12:13], 0x40080
	v_lshl_add_u64 v[192:193], v[190:191], 0, s[12:13]
	s_add_u32 m0, s98, 0x9000
	s_nop 0
	global_load_lds_dwordx4 v[192:193], off
	s_mov_b64 s[12:13], 0x60080
	v_lshl_add_u64 v[192:193], v[190:191], 0, s[12:13]
	s_add_u32 m0, s98, 0xb000
	s_nop 0
	global_load_lds_dwordx4 v[192:193], off
	s_add_u32 s7, s7, 0xd000
	s_cmp_eq_u32 s7, 0x27000
	s_cselect_b32 s7, 0, s7
	s_add_u32 s10, s10, 0x80
	s_addc_u32 s11, s11, 0
	s_cmpk_eq_i32 s10, 0x700
	s_cbranch_scc0 .Lg160i_p
	v_add_u32_e32 v168, s7, v95
	v_add_u32_e32 v169, s7, v97
	v_add_u32_e32 v196, v168, v99
	v_add_u32_e32 v200, v169, v99
	v_add_u32_e32 v168, v168, v98
	v_add_u32_e32 v169, v169, v98
	s_waitcnt vmcnt(7) lgkmcnt(0)
	s_barrier
	ds_read_b128 v[156:159], v168 offset:20480
	ds_read_b128 v[160:163], v168 offset:22528
	ds_read_b128 v[112:115], v169
	ds_read_b128 v[116:119], v169 offset:2048
	ds_read_b128 v[120:123], v169 offset:4096
	ds_read_b128 v[124:127], v169 offset:6144
	ds_read_b128 v[132:135], v169 offset:8192
	ds_read_b128 v[136:139], v169 offset:10240
	ds_read_b128 v[140:143], v169 offset:12288
	ds_read_b128 v[144:147], v169 offset:14336
	ds_read_b128 v[148:151], v169 offset:16384
	ds_read_b128 v[152:155], v169 offset:18432
	s_waitcnt lgkmcnt(9)
	v_mfma_f32_16x16x32_bf16 v[76:79], v[156:159], v[112:115], v[76:79]
	v_mfma_f32_16x16x32_bf16 v[72:75], v[160:163], v[112:115], v[72:75]
	ds_read_b128 v[204:207], v196 offset:20480
	s_waitcnt lgkmcnt(9)
	v_mfma_f32_16x16x32_bf16 v[68:71], v[156:159], v[116:119], v[68:71]
	v_mfma_f32_16x16x32_bf16 v[64:67], v[160:163], v[116:119], v[64:67]
	ds_read_b128 v[208:211], v196 offset:22528
	s_waitcnt lgkmcnt(9)
	v_mfma_f32_16x16x32_bf16 v[60:63], v[156:159], v[120:123], v[60:63]
	v_mfma_f32_16x16x32_bf16 v[56:59], v[160:163], v[120:123], v[56:59]
	ds_read_b128 v[164:167], v200
	s_waitcnt lgkmcnt(9)
	v_mfma_f32_16x16x32_bf16 v[52:55], v[156:159], v[124:127], v[52:55]
	v_mfma_f32_16x16x32_bf16 v[48:51], v[160:163], v[124:127], v[48:51]
	ds_read_b128 v[168:171], v200 offset:2048
	s_waitcnt lgkmcnt(9)
	v_mfma_f32_16x16x32_bf16 v[44:47], v[156:159], v[132:135], v[44:47]
	v_mfma_f32_16x16x32_bf16 v[40:43], v[160:163], v[132:135], v[40:43]
	ds_read_b128 v[172:175], v200 offset:4096
	s_waitcnt lgkmcnt(9)
	v_mfma_f32_16x16x32_bf16 v[36:39], v[156:159], v[136:139], v[36:39]
	v_mfma_f32_16x16x32_bf16 v[32:35], v[160:163], v[136:139], v[32:35]
	ds_read_b128 v[176:179], v200 offset:6144
	s_waitcnt lgkmcnt(9)
	v_mfma_f32_16x16x32_bf16 v[28:31], v[156:159], v[140:143], v[28:31]
	v_mfma_f32_16x16x32_bf16 v[24:27], v[160:163], v[140:143], v[24:27]
	ds_read_b128 v[180:183], v200 offset:8192
	s_waitcnt lgkmcnt(9)
	v_mfma_f32_16x16x32_bf16 v[20:23], v[156:159], v[144:147], v[20:23]
	v_mfma_f32_16x16x32_bf16 v[16:19], v[160:163], v[144:147], v[16:19]
	ds_read_b128 v[184:187], v200 offset:10240
	s_waitcnt lgkmcnt(9)
	v_mfma_f32_16x16x32_bf16 v[12:15], v[156:159], v[148:151], v[12:15]
	v_mfma_f32_16x16x32_bf16 v[8:11], v[160:163], v[148:151], v[8:11]
	ds_read_b128 v[188:191], v200 offset:12288
	s_waitcnt lgkmcnt(9)
	v_mfma_f32_16x16x32_bf16 v[4:7], v[156:159], v[152:155], v[4:7]
	v_mfma_f32_16x16x32_bf16 v[0:3], v[160:163], v[152:155], v[0:3]
	ds_read_b128 v[192:195], v200 offset:14336
	ds_read_b128 v[196:199], v200 offset:16384
	ds_read_b128 v[200:203], v200 offset:18432
	s_waitcnt lgkmcnt(9)
	v_mfma_f32_16x16x32_bf16 v[76:79], v[204:207], v[164:167], v[76:79]
	v_mfma_f32_16x16x32_bf16 v[72:75], v[208:211], v[164:167], v[72:75]
	s_waitcnt lgkmcnt(8)
	v_mfma_f32_16x16x32_bf16 v[68:71], v[204:207], v[168:171], v[68:71]
	v_mfma_f32_16x16x32_bf16 v[64:67], v[208:211], v[168:171], v[64:67]
	s_waitcnt lgkmcnt(7)
	v_mfma_f32_16x16x32_bf16 v[60:63], v[204:207], v[172:175], v[60:63]
	v_mfma_f32_16x16x32_bf16 v[56:59], v[208:211], v[172:175], v[56:59]
	s_waitcnt lgkmcnt(6)
	v_mfma_f32_16x16x32_bf16 v[52:55], v[204:207], v[176:179], v[52:55]
	v_mfma_f32_16x16x32_bf16 v[48:51], v[208:211], v[176:179], v[48:51]
	s_waitcnt lgkmcnt(5)
	v_mfma_f32_16x16x32_bf16 v[44:47], v[204:207], v[180:183], v[44:47]
	v_mfma_f32_16x16x32_bf16 v[40:43], v[208:211], v[180:183], v[40:43]
	s_waitcnt lgkmcnt(4)
	v_mfma_f32_16x16x32_bf16 v[36:39], v[204:207], v[184:187], v[36:39]
	v_mfma_f32_16x16x32_bf16 v[32:35], v[208:211], v[184:187], v[32:35]
	s_waitcnt lgkmcnt(3)
	v_mfma_f32_16x16x32_bf16 v[28:31], v[204:207], v[188:191], v[28:31]
	v_mfma_f32_16x16x32_bf16 v[24:27], v[208:211], v[188:191], v[24:27]
	s_waitcnt lgkmcnt(2)
	v_mfma_f32_16x16x32_bf16 v[20:23], v[204:207], v[192:195], v[20:23]
	v_mfma_f32_16x16x32_bf16 v[16:19], v[208:211], v[192:195], v[16:19]
	s_waitcnt lgkmcnt(1)
	v_mfma_f32_16x16x32_bf16 v[12:15], v[204:207], v[196:199], v[12:15]
	v_mfma_f32_16x16x32_bf16 v[8:11], v[208:211], v[196:199], v[8:11]
	s_waitcnt lgkmcnt(0)
	v_mfma_f32_16x16x32_bf16 v[4:7], v[204:207], v[200:203], v[4:7]
	v_mfma_f32_16x16x32_bf16 v[0:3], v[208:211], v[200:203], v[0:3]
	s_add_u32 s7, s7, 0xd000
	s_cmp_eq_u32 s7, 0x27000
	s_cselect_b32 s7, 0, s7
	v_add_u32_e32 v168, s7, v95
	v_add_u32_e32 v169, s7, v97
	v_add_u32_e32 v196, v168, v99
	v_add_u32_e32 v200, v169, v99
	v_add_u32_e32 v168, v168, v98
	v_add_u32_e32 v169, v169, v98
	s_waitcnt vmcnt(0) lgkmcnt(0)
	s_barrier
	ds_read_b128 v[156:159], v168 offset:20480
	ds_read_b128 v[160:163], v168 offset:22528
	ds_read_b128 v[112:115], v169
	ds_read_b128 v[116:119], v169 offset:2048
	ds_read_b128 v[120:123], v169 offset:4096
	ds_read_b128 v[124:127], v169 offset:6144
	ds_read_b128 v[132:135], v169 offset:8192
	ds_read_b128 v[136:139], v169 offset:10240
	ds_read_b128 v[140:143], v169 offset:12288
	ds_read_b128 v[144:147], v169 offset:14336
	ds_read_b128 v[148:151], v169 offset:16384
	ds_read_b128 v[152:155], v169 offset:18432
	s_waitcnt lgkmcnt(9)
	v_mfma_f32_16x16x32_bf16 v[76:79], v[156:159], v[112:115], v[76:79]
	v_mfma_f32_16x16x32_bf16 v[72:75], v[160:163], v[112:115], v[72:75]
	ds_read_b128 v[204:207], v196 offset:20480
	s_waitcnt lgkmcnt(9)
	v_mfma_f32_16x16x32_bf16 v[68:71], v[156:159], v[116:119], v[68:71]
	v_mfma_f32_16x16x32_bf16 v[64:67], v[160:163], v[116:119], v[64:67]
	ds_read_b128 v[208:211], v196 offset:22528
	s_waitcnt lgkmcnt(9)
	v_mfma_f32_16x16x32_bf16 v[60:63], v[156:159], v[120:123], v[60:63]
	v_mfma_f32_16x16x32_bf16 v[56:59], v[160:163], v[120:123], v[56:59]
	ds_read_b128 v[164:167], v200
	s_waitcnt lgkmcnt(9)
	v_mfma_f32_16x16x32_bf16 v[52:55], v[156:159], v[124:127], v[52:55]
	v_mfma_f32_16x16x32_bf16 v[48:51], v[160:163], v[124:127], v[48:51]
	ds_read_b128 v[168:171], v200 offset:2048
	s_waitcnt lgkmcnt(9)
	v_mfma_f32_16x16x32_bf16 v[44:47], v[156:159], v[132:135], v[44:47]
	v_mfma_f32_16x16x32_bf16 v[40:43], v[160:163], v[132:135], v[40:43]
	ds_read_b128 v[172:175], v200 offset:4096
	s_waitcnt lgkmcnt(9)
	v_mfma_f32_16x16x32_bf16 v[36:39], v[156:159], v[136:139], v[36:39]
	v_mfma_f32_16x16x32_bf16 v[32:35], v[160:163], v[136:139], v[32:35]
	ds_read_b128 v[176:179], v200 offset:6144
	s_waitcnt lgkmcnt(9)
	v_mfma_f32_16x16x32_bf16 v[28:31], v[156:159], v[140:143], v[28:31]
	v_mfma_f32_16x16x32_bf16 v[24:27], v[160:163], v[140:143], v[24:27]
	ds_read_b128 v[180:183], v200 offset:8192
	s_waitcnt lgkmcnt(9)
	v_mfma_f32_16x16x32_bf16 v[20:23], v[156:159], v[144:147], v[20:23]
	v_mfma_f32_16x16x32_bf16 v[16:19], v[160:163], v[144:147], v[16:19]
	ds_read_b128 v[184:187], v200 offset:10240
	s_waitcnt lgkmcnt(9)
	v_mfma_f32_16x16x32_bf16 v[12:15], v[156:159], v[148:151], v[12:15]
	v_mfma_f32_16x16x32_bf16 v[8:11], v[160:163], v[148:151], v[8:11]
	ds_read_b128 v[188:191], v200 offset:12288
	s_waitcnt lgkmcnt(9)
	v_mfma_f32_16x16x32_bf16 v[4:7], v[156:159], v[152:155], v[4:7]
	v_mfma_f32_16x16x32_bf16 v[0:3], v[160:163], v[152:155], v[0:3]
	ds_read_b128 v[192:195], v200 offset:14336
	ds_read_b128 v[196:199], v200 offset:16384
	ds_read_b128 v[200:203], v200 offset:18432
	s_waitcnt lgkmcnt(9)
	v_mfma_f32_16x16x32_bf16 v[76:79], v[204:207], v[164:167], v[76:79]
	v_mfma_f32_16x16x32_bf16 v[72:75], v[208:211], v[164:167], v[72:75]
	s_waitcnt lgkmcnt(8)
	v_mfma_f32_16x16x32_bf16 v[68:71], v[204:207], v[168:171], v[68:71]
	v_mfma_f32_16x16x32_bf16 v[64:67], v[208:211], v[168:171], v[64:67]
	s_waitcnt lgkmcnt(7)
	v_mfma_f32_16x16x32_bf16 v[60:63], v[204:207], v[172:175], v[60:63]
	v_mfma_f32_16x16x32_bf16 v[56:59], v[208:211], v[172:175], v[56:59]
	s_waitcnt lgkmcnt(6)
	v_mfma_f32_16x16x32_bf16 v[52:55], v[204:207], v[176:179], v[52:55]
	v_mfma_f32_16x16x32_bf16 v[48:51], v[208:211], v[176:179], v[48:51]
	s_waitcnt lgkmcnt(5)
	v_mfma_f32_16x16x32_bf16 v[44:47], v[204:207], v[180:183], v[44:47]
	v_mfma_f32_16x16x32_bf16 v[40:43], v[208:211], v[180:183], v[40:43]
	s_waitcnt lgkmcnt(4)
	v_mfma_f32_16x16x32_bf16 v[36:39], v[204:207], v[184:187], v[36:39]
	v_mfma_f32_16x16x32_bf16 v[32:35], v[208:211], v[184:187], v[32:35]
	s_waitcnt lgkmcnt(3)
	v_mfma_f32_16x16x32_bf16 v[28:31], v[204:207], v[188:191], v[28:31]
	v_mfma_f32_16x16x32_bf16 v[24:27], v[208:211], v[188:191], v[24:27]
	s_waitcnt lgkmcnt(2)
	v_mfma_f32_16x16x32_bf16 v[20:23], v[204:207], v[192:195], v[20:23]
	v_mfma_f32_16x16x32_bf16 v[16:19], v[208:211], v[192:195], v[16:19]
	s_waitcnt lgkmcnt(1)
	v_mfma_f32_16x16x32_bf16 v[12:15], v[204:207], v[196:199], v[12:15]
	v_mfma_f32_16x16x32_bf16 v[8:11], v[208:211], v[196:199], v[8:11]
	s_waitcnt lgkmcnt(0)
	v_mfma_f32_16x16x32_bf16 v[4:7], v[204:207], v[200:203], v[4:7]
	v_mfma_f32_16x16x32_bf16 v[0:3], v[208:211], v[200:203], v[0:3]
	s_add_u32 s7, s7, 0xd000
	s_cmp_eq_u32 s7, 0x27000
	s_cselect_b32 s7, 0, s7
	s_branch .Lg160i_epi
.Lg160i_q:
	s_add_u32 s12, s7, 0x1a000
	s_cmp_ge_u32 s12, 0x27000
	s_cselect_b32 s13, 0x27000, 0
	s_sub_u32 s12, s12, s13
	v_add_u32_e32 v172, s12, v96
	s_add_u32 s12, s10, 0x80
	s_addc_u32 s13, s11, 0
	v_lshl_add_u64 v[92:93], v[88:89], 0, s[12:13]
	v_lshl_add_u64 v[190:191], v[90:91], 0, s[12:13]
	v_readfirstlane_b32 s98, v172
	v_add_u32_e32 v168, s7, v95
	v_add_u32_e32 v169, s7, v97
	v_add_u32_e32 v196, v168, v99
	v_add_u32_e32 v200, v169, v99
	v_add_u32_e32 v168, v168, v98
	v_add_u32_e32 v169, v169, v98
	s_waitcnt vmcnt(6) lgkmcnt(0)
	s_barrier
	v_lshl_add_u64 v[192:193], v[92:93], 0, s[78:79]
	s_mov_b32 m0, s98
	s_nop 0
	global_load_lds_dwordx4 v[192:193], off
	v_lshl_add_u64 v[192:193], v[92:93], 0, s[80:81]
	s_add_u32 m0, s98, 0x2000
	s_nop 0
	global_load_lds_dwordx4 v[192:193], off
	s_mov_b64 s[12:13], 0x80
	v_lshl_add_u64 v[192:193], v[190:191], 0, s[12:13]
	s_add_u32 m0, s98, 0x5000
	s_nop 0
	global_load_lds_dwordx4 v[192:193], off
	s_mov_b64 s[12:13], 0x20080
	v_lshl_add_u64 v[192:193], v[190:191], 0, s[12:13]
	s_add_u32 m0, s98, 0x7000
	s_nop 0
	global_load_lds_dwordx4 v[192:193], off
	s_mov_b64 s[12:13], 0x40080
	v_lshl_add_u64 v[192:193], v[190:191], 0, s[12:13]
	s_add_u32 m0, s98, 0x9000
	s_nop 0
	global_load_lds_dwordx4 v[192:193], off
	s_mov_b64 s[12:13], 0x60080
	v_lshl_add_u64 v[192:193], v[190:191], 0, s[12:13]
	s_add_u32 m0, s98, 0xb000
	s_nop 0
	global_load_lds_dwordx4 v[192:193], off
	ds_read_b128 v[156:159], v168 offset:20480
	ds_read_b128 v[160:163], v168 offset:22528
	ds_read_b128 v[112:115], v169
	ds_read_b128 v[116:119], v169 offset:2048
	ds_read_b128 v[120:123], v169 offset:4096
	ds_read_b128 v[124:127], v169 offset:6144
	ds_read_b128 v[132:135], v169 offset:8192
	ds_read_b128 v[136:139], v169 offset:10240
	ds_read_b128 v[140:143], v169 offset:12288
	ds_read_b128 v[144:147], v169 offset:14336
	ds_read_b128 v[148:151], v169 offset:16384
	ds_read_b128 v[152:155], v169 offset:18432
	s_waitcnt lgkmcnt(9)
	v_mfma_f32_16x16x32_bf16 v[76:79], v[156:159], v[112:115], v[76:79]
	v_mfma_f32_16x16x32_bf16 v[72:75], v[160:163], v[112:115], v[72:75]
	ds_read_b128 v[204:207], v196 offset:20480
	s_waitcnt lgkmcnt(9)
	v_mfma_f32_16x16x32_bf16 v[68:71], v[156:159], v[116:119], v[68:71]
	v_mfma_f32_16x16x32_bf16 v[64:67], v[160:163], v[116:119], v[64:67]
	ds_read_b128 v[208:211], v196 offset:22528
	s_waitcnt lgkmcnt(9)
	v_mfma_f32_16x16x32_bf16 v[60:63], v[156:159], v[120:123], v[60:63]
	v_mfma_f32_16x16x32_bf16 v[56:59], v[160:163], v[120:123], v[56:59]
	ds_read_b128 v[164:167], v200
	s_waitcnt lgkmcnt(9)
	v_mfma_f32_16x16x32_bf16 v[52:55], v[156:159], v[124:127], v[52:55]
	v_mfma_f32_16x16x32_bf16 v[48:51], v[160:163], v[124:127], v[48:51]
	ds_read_b128 v[168:171], v200 offset:2048
	s_waitcnt lgkmcnt(9)
	v_mfma_f32_16x16x32_bf16 v[44:47], v[156:159], v[132:135], v[44:47]
	v_mfma_f32_16x16x32_bf16 v[40:43], v[160:163], v[132:135], v[40:43]
	ds_read_b128 v[172:175], v200 offset:4096
	s_waitcnt lgkmcnt(9)
	v_mfma_f32_16x16x32_bf16 v[36:39], v[156:159], v[136:139], v[36:39]
	v_mfma_f32_16x16x32_bf16 v[32:35], v[160:163], v[136:139], v[32:35]
	ds_read_b128 v[176:179], v200 offset:6144
	s_waitcnt lgkmcnt(9)
	v_mfma_f32_16x16x32_bf16 v[28:31], v[156:159], v[140:143], v[28:31]
	v_mfma_f32_16x16x32_bf16 v[24:27], v[160:163], v[140:143], v[24:27]
	ds_read_b128 v[180:183], v200 offset:8192
	s_waitcnt lgkmcnt(9)
	v_mfma_f32_16x16x32_bf16 v[20:23], v[156:159], v[144:147], v[20:23]
	v_mfma_f32_16x16x32_bf16 v[16:19], v[160:163], v[144:147], v[16:19]
	ds_read_b128 v[184:187], v200 offset:10240
	s_waitcnt lgkmcnt(9)
	v_mfma_f32_16x16x32_bf16 v[12:15], v[156:159], v[148:151], v[12:15]
	v_mfma_f32_16x16x32_bf16 v[8:11], v[160:163], v[148:151], v[8:11]
	ds_read_b128 v[188:191], v200 offset:12288
	s_waitcnt lgkmcnt(9)
	v_mfma_f32_16x16x32_bf16 v[4:7], v[156:159], v[152:155], v[4:7]
	v_mfma_f32_16x16x32_bf16 v[0:3], v[160:163], v[152:155], v[0:3]
	ds_read_b128 v[192:195], v200 offset:14336
	ds_read_b128 v[196:199], v200 offset:16384
	ds_read_b128 v[200:203], v200 offset:18432
	s_waitcnt lgkmcnt(9)
	v_mfma_f32_16x16x32_bf16 v[76:79], v[204:207], v[164:167], v[76:79]
	v_mfma_f32_16x16x32_bf16 v[72:75], v[208:211], v[164:167], v[72:75]
	s_waitcnt lgkmcnt(8)
	v_mfma_f32_16x16x32_bf16 v[68:71], v[204:207], v[168:171], v[68:71]
	v_mfma_f32_16x16x32_bf16 v[64:67], v[208:211], v[168:171], v[64:67]
	s_waitcnt lgkmcnt(7)
	v_mfma_f32_16x16x32_bf16 v[60:63], v[204:207], v[172:175], v[60:63]
	v_mfma_f32_16x16x32_bf16 v[56:59], v[208:211], v[172:175], v[56:59]
	s_waitcnt lgkmcnt(6)
	v_mfma_f32_16x16x32_bf16 v[52:55], v[204:207], v[176:179], v[52:55]
	v_mfma_f32_16x16x32_bf16 v[48:51], v[208:211], v[176:179], v[48:51]
	s_waitcnt lgkmcnt(5)
	v_mfma_f32_16x16x32_bf16 v[44:47], v[204:207], v[180:183], v[44:47]
	v_mfma_f32_16x16x32_bf16 v[40:43], v[208:211], v[180:183], v[40:43]
	s_waitcnt lgkmcnt(4)
	v_mfma_f32_16x16x32_bf16 v[36:39], v[204:207], v[184:187], v[36:39]
	v_mfma_f32_16x16x32_bf16 v[32:35], v[208:211], v[184:187], v[32:35]
	s_waitcnt lgkmcnt(3)
	v_mfma_f32_16x16x32_bf16 v[28:31], v[204:207], v[188:191], v[28:31]
	v_mfma_f32_16x16x32_bf16 v[24:27], v[208:211], v[188:191], v[24:27]
	s_waitcnt lgkmcnt(2)
	v_mfma_f32_16x16x32_bf16 v[20:23], v[204:207], v[192:195], v[20:23]
	v_mfma_f32_16x16x32_bf16 v[16:19], v[208:211], v[192:195], v[16:19]
	s_waitcnt lgkmcnt(1)
	v_mfma_f32_16x16x32_bf16 v[12:15], v[204:207], v[196:199], v[12:15]
	v_mfma_f32_16x16x32_bf16 v[8:11], v[208:211], v[196:199], v[8:11]
	s_waitcnt lgkmcnt(0)
	v_mfma_f32_16x16x32_bf16 v[4:7], v[204:207], v[200:203], v[4:7]
	v_mfma_f32_16x16x32_bf16 v[0:3], v[208:211], v[200:203], v[0:3]
	s_add_u32 s7, s7, 0xd000
	s_cmp_eq_u32 s7, 0x27000
	s_cselect_b32 s7, 0, s7
	s_add_u32 s10, s10, 0x80
	s_addc_u32 s11, s11, 0
	s_cmpk_eq_i32 s10, 0x700
	s_cbranch_scc0 .Lg160i_q
	v_add_u32_e32 v168, s7, v95
	v_add_u32_e32 v169, s7, v97
	v_add_u32_e32 v196, v168, v99
	v_add_u32_e32 v200, v169, v99
	v_add_u32_e32 v168, v168, v98
	v_add_u32_e32 v169, v169, v98
	s_waitcnt vmcnt(6) lgkmcnt(0)
	s_barrier
	ds_read_b128 v[156:159], v168 offset:20480
	ds_read_b128 v[160:163], v168 offset:22528
	ds_read_b128 v[112:115], v169
	ds_read_b128 v[116:119], v169 offset:2048
	ds_read_b128 v[120:123], v169 offset:4096
	ds_read_b128 v[124:127], v169 offset:6144
	ds_read_b128 v[132:135], v169 offset:8192
	ds_read_b128 v[136:139], v169 offset:10240
	ds_read_b128 v[140:143], v169 offset:12288
	ds_read_b128 v[144:147], v169 offset:14336
	ds_read_b128 v[148:151], v169 offset:16384
	ds_read_b128 v[152:155], v169 offset:18432
	s_waitcnt lgkmcnt(9)
	v_mfma_f32_16x16x32_bf16 v[76:79], v[156:159], v[112:115], v[76:79]
	v_mfma_f32_16x16x32_bf16 v[72:75], v[160:163], v[112:115], v[72:75]
	ds_read_b128 v[204:207], v196 offset:20480
	s_waitcnt lgkmcnt(9)
	v_mfma_f32_16x16x32_bf16 v[68:71], v[156:159], v[116:119], v[68:71]
	v_mfma_f32_16x16x32_bf16 v[64:67], v[160:163], v[116:119], v[64:67]
	ds_read_b128 v[208:211], v196 offset:22528
	s_waitcnt lgkmcnt(9)
	v_mfma_f32_16x16x32_bf16 v[60:63], v[156:159], v[120:123], v[60:63]
	v_mfma_f32_16x16x32_bf16 v[56:59], v[160:163], v[120:123], v[56:59]
	ds_read_b128 v[164:167], v200
	s_waitcnt lgkmcnt(9)
	v_mfma_f32_16x16x32_bf16 v[52:55], v[156:159], v[124:127], v[52:55]
	v_mfma_f32_16x16x32_bf16 v[48:51], v[160:163], v[124:127], v[48:51]
	ds_read_b128 v[168:171], v200 offset:2048
	s_waitcnt lgkmcnt(9)
	v_mfma_f32_16x16x32_bf16 v[44:47], v[156:159], v[132:135], v[44:47]
	v_mfma_f32_16x16x32_bf16 v[40:43], v[160:163], v[132:135], v[40:43]
	ds_read_b128 v[172:175], v200 offset:4096
	s_waitcnt lgkmcnt(9)
	v_mfma_f32_16x16x32_bf16 v[36:39], v[156:159], v[136:139], v[36:39]
	v_mfma_f32_16x16x32_bf16 v[32:35], v[160:163], v[136:139], v[32:35]
	ds_read_b128 v[176:179], v200 offset:6144
	s_waitcnt lgkmcnt(9)
	v_mfma_f32_16x16x32_bf16 v[28:31], v[156:159], v[140:143], v[28:31]
	v_mfma_f32_16x16x32_bf16 v[24:27], v[160:163], v[140:143], v[24:27]
	ds_read_b128 v[180:183], v200 offset:8192
	s_waitcnt lgkmcnt(9)
	v_mfma_f32_16x16x32_bf16 v[20:23], v[156:159], v[144:147], v[20:23]
	v_mfma_f32_16x16x32_bf16 v[16:19], v[160:163], v[144:147], v[16:19]
	ds_read_b128 v[184:187], v200 offset:10240
	s_waitcnt lgkmcnt(9)
	v_mfma_f32_16x16x32_bf16 v[12:15], v[156:159], v[148:151], v[12:15]
	v_mfma_f32_16x16x32_bf16 v[8:11], v[160:163], v[148:151], v[8:11]
	ds_read_b128 v[188:191], v200 offset:12288
	s_waitcnt lgkmcnt(9)
	v_mfma_f32_16x16x32_bf16 v[4:7], v[156:159], v[152:155], v[4:7]
	v_mfma_f32_16x16x32_bf16 v[0:3], v[160:163], v[152:155], v[0:3]
	ds_read_b128 v[192:195], v200 offset:14336
	ds_read_b128 v[196:199], v200 offset:16384
	ds_read_b128 v[200:203], v200 offset:18432
	s_waitcnt lgkmcnt(9)
	v_mfma_f32_16x16x32_bf16 v[76:79], v[204:207], v[164:167], v[76:79]
	v_mfma_f32_16x16x32_bf16 v[72:75], v[208:211], v[164:167], v[72:75]
	s_waitcnt lgkmcnt(8)
	v_mfma_f32_16x16x32_bf16 v[68:71], v[204:207], v[168:171], v[68:71]
	v_mfma_f32_16x16x32_bf16 v[64:67], v[208:211], v[168:171], v[64:67]
	s_waitcnt lgkmcnt(7)
	v_mfma_f32_16x16x32_bf16 v[60:63], v[204:207], v[172:175], v[60:63]
	v_mfma_f32_16x16x32_bf16 v[56:59], v[208:211], v[172:175], v[56:59]
	s_waitcnt lgkmcnt(6)
	v_mfma_f32_16x16x32_bf16 v[52:55], v[204:207], v[176:179], v[52:55]
	v_mfma_f32_16x16x32_bf16 v[48:51], v[208:211], v[176:179], v[48:51]
	s_waitcnt lgkmcnt(5)
	v_mfma_f32_16x16x32_bf16 v[44:47], v[204:207], v[180:183], v[44:47]
	v_mfma_f32_16x16x32_bf16 v[40:43], v[208:211], v[180:183], v[40:43]
	s_waitcnt lgkmcnt(4)
	v_mfma_f32_16x16x32_bf16 v[36:39], v[204:207], v[184:187], v[36:39]
	v_mfma_f32_16x16x32_bf16 v[32:35], v[208:211], v[184:187], v[32:35]
	s_waitcnt lgkmcnt(3)
	v_mfma_f32_16x16x32_bf16 v[28:31], v[204:207], v[188:191], v[28:31]
	v_mfma_f32_16x16x32_bf16 v[24:27], v[208:211], v[188:191], v[24:27]
	s_waitcnt lgkmcnt(2)
	v_mfma_f32_16x16x32_bf16 v[20:23], v[204:207], v[192:195], v[20:23]
	v_mfma_f32_16x16x32_bf16 v[16:19], v[208:211], v[192:195], v[16:19]
	s_waitcnt lgkmcnt(1)
	v_mfma_f32_16x16x32_bf16 v[12:15], v[204:207], v[196:199], v[12:15]
	v_mfma_f32_16x16x32_bf16 v[8:11], v[208:211], v[196:199], v[8:11]
	s_waitcnt lgkmcnt(0)
	v_mfma_f32_16x16x32_bf16 v[4:7], v[204:207], v[200:203], v[4:7]
	v_mfma_f32_16x16x32_bf16 v[0:3], v[208:211], v[200:203], v[0:3]
	s_add_u32 s7, s7, 0xd000
	s_cmp_eq_u32 s7, 0x27000
	s_cselect_b32 s7, 0, s7
	v_add_u32_e32 v168, s7, v95
	v_add_u32_e32 v169, s7, v97
	v_add_u32_e32 v196, v168, v99
	v_add_u32_e32 v200, v169, v99
	v_add_u32_e32 v168, v168, v98
	v_add_u32_e32 v169, v169, v98
	s_waitcnt vmcnt(0) lgkmcnt(0)
	s_barrier
	ds_read_b128 v[156:159], v168 offset:20480
	ds_read_b128 v[160:163], v168 offset:22528
	ds_read_b128 v[112:115], v169
	ds_read_b128 v[116:119], v169 offset:2048
	ds_read_b128 v[120:123], v169 offset:4096
	ds_read_b128 v[124:127], v169 offset:6144
	ds_read_b128 v[132:135], v169 offset:8192
	ds_read_b128 v[136:139], v169 offset:10240
	ds_read_b128 v[140:143], v169 offset:12288
	ds_read_b128 v[144:147], v169 offset:14336
	ds_read_b128 v[148:151], v169 offset:16384
	ds_read_b128 v[152:155], v169 offset:18432
	s_waitcnt lgkmcnt(9)
	v_mfma_f32_16x16x32_bf16 v[76:79], v[156:159], v[112:115], v[76:79]
	v_mfma_f32_16x16x32_bf16 v[72:75], v[160:163], v[112:115], v[72:75]
	ds_read_b128 v[204:207], v196 offset:20480
	s_waitcnt lgkmcnt(9)
	v_mfma_f32_16x16x32_bf16 v[68:71], v[156:159], v[116:119], v[68:71]
	v_mfma_f32_16x16x32_bf16 v[64:67], v[160:163], v[116:119], v[64:67]
	ds_read_b128 v[208:211], v196 offset:22528
	s_waitcnt lgkmcnt(9)
	v_mfma_f32_16x16x32_bf16 v[60:63], v[156:159], v[120:123], v[60:63]
	v_mfma_f32_16x16x32_bf16 v[56:59], v[160:163], v[120:123], v[56:59]
	ds_read_b128 v[164:167], v200
	s_waitcnt lgkmcnt(9)
	v_mfma_f32_16x16x32_bf16 v[52:55], v[156:159], v[124:127], v[52:55]
	v_mfma_f32_16x16x32_bf16 v[48:51], v[160:163], v[124:127], v[48:51]
	ds_read_b128 v[168:171], v200 offset:2048
	s_waitcnt lgkmcnt(9)
	v_mfma_f32_16x16x32_bf16 v[44:47], v[156:159], v[132:135], v[44:47]
	v_mfma_f32_16x16x32_bf16 v[40:43], v[160:163], v[132:135], v[40:43]
	ds_read_b128 v[172:175], v200 offset:4096
	s_waitcnt lgkmcnt(9)
	v_mfma_f32_16x16x32_bf16 v[36:39], v[156:159], v[136:139], v[36:39]
	v_mfma_f32_16x16x32_bf16 v[32:35], v[160:163], v[136:139], v[32:35]
	ds_read_b128 v[176:179], v200 offset:6144
	s_waitcnt lgkmcnt(9)
	v_mfma_f32_16x16x32_bf16 v[28:31], v[156:159], v[140:143], v[28:31]
	v_mfma_f32_16x16x32_bf16 v[24:27], v[160:163], v[140:143], v[24:27]
	ds_read_b128 v[180:183], v200 offset:8192
	s_waitcnt lgkmcnt(9)
	v_mfma_f32_16x16x32_bf16 v[20:23], v[156:159], v[144:147], v[20:23]
	v_mfma_f32_16x16x32_bf16 v[16:19], v[160:163], v[144:147], v[16:19]
	ds_read_b128 v[184:187], v200 offset:10240
	s_waitcnt lgkmcnt(9)
	v_mfma_f32_16x16x32_bf16 v[12:15], v[156:159], v[148:151], v[12:15]
	v_mfma_f32_16x16x32_bf16 v[8:11], v[160:163], v[148:151], v[8:11]
	ds_read_b128 v[188:191], v200 offset:12288
	s_waitcnt lgkmcnt(9)
	v_mfma_f32_16x16x32_bf16 v[4:7], v[156:159], v[152:155], v[4:7]
	v_mfma_f32_16x16x32_bf16 v[0:3], v[160:163], v[152:155], v[0:3]
	ds_read_b128 v[192:195], v200 offset:14336
	ds_read_b128 v[196:199], v200 offset:16384
	ds_read_b128 v[200:203], v200 offset:18432
	s_waitcnt lgkmcnt(9)
	v_mfma_f32_16x16x32_bf16 v[76:79], v[204:207], v[164:167], v[76:79]
	v_mfma_f32_16x16x32_bf16 v[72:75], v[208:211], v[164:167], v[72:75]
	s_waitcnt lgkmcnt(8)
	v_mfma_f32_16x16x32_bf16 v[68:71], v[204:207], v[168:171], v[68:71]
	v_mfma_f32_16x16x32_bf16 v[64:67], v[208:211], v[168:171], v[64:67]
	s_waitcnt lgkmcnt(7)
	v_mfma_f32_16x16x32_bf16 v[60:63], v[204:207], v[172:175], v[60:63]
	v_mfma_f32_16x16x32_bf16 v[56:59], v[208:211], v[172:175], v[56:59]
	s_waitcnt lgkmcnt(6)
	v_mfma_f32_16x16x32_bf16 v[52:55], v[204:207], v[176:179], v[52:55]
	v_mfma_f32_16x16x32_bf16 v[48:51], v[208:211], v[176:179], v[48:51]
	s_waitcnt lgkmcnt(5)
	v_mfma_f32_16x16x32_bf16 v[44:47], v[204:207], v[180:183], v[44:47]
	v_mfma_f32_16x16x32_bf16 v[40:43], v[208:211], v[180:183], v[40:43]
	s_waitcnt lgkmcnt(4)
	v_mfma_f32_16x16x32_bf16 v[36:39], v[204:207], v[184:187], v[36:39]
	v_mfma_f32_16x16x32_bf16 v[32:35], v[208:211], v[184:187], v[32:35]
	s_waitcnt lgkmcnt(3)
	v_mfma_f32_16x16x32_bf16 v[28:31], v[204:207], v[188:191], v[28:31]
	v_mfma_f32_16x16x32_bf16 v[24:27], v[208:211], v[188:191], v[24:27]
	s_waitcnt lgkmcnt(2)
	v_mfma_f32_16x16x32_bf16 v[20:23], v[204:207], v[192:195], v[20:23]
	v_mfma_f32_16x16x32_bf16 v[16:19], v[208:211], v[192:195], v[16:19]
	s_waitcnt lgkmcnt(1)
	v_mfma_f32_16x16x32_bf16 v[12:15], v[204:207], v[196:199], v[12:15]
	v_mfma_f32_16x16x32_bf16 v[8:11], v[208:211], v[196:199], v[8:11]
	s_waitcnt lgkmcnt(0)
	v_mfma_f32_16x16x32_bf16 v[4:7], v[204:207], v[200:203], v[4:7]
	v_mfma_f32_16x16x32_bf16 v[0:3], v[208:211], v[200:203], v[0:3]
	s_add_u32 s7, s7, 0xd000
	s_cmp_eq_u32 s7, 0x27000
	s_cselect_b32 s7, 0, s7
	s_branch .Lg160i_epi

.Lg160o_pskip:
	s_or_b64 exec, exec, s[100:101]
	s_mov_b64 s[12:13], 0x360080
	v_lshl_add_u64 v[188:189], v[92:93], 0, s[12:13]
	s_add_u32 m0, s98, 0x5000
	s_nop 0
	global_load_lds_dwordx4 v[188:189], off
	s_mov_b64 s[12:13], 0x380080
	v_lshl_add_u64 v[188:189], v[92:93], 0, s[12:13]
	s_add_u32 m0, s98, 0x7000
	s_nop 0
	global_load_lds_dwordx4 v[188:189], off
	s_mov_b64 s[12:13], 0x3a0080
	v_lshl_add_u64 v[188:189], v[92:93], 0, s[12:13]
	s_add_u32 m0, s98, 0x9000
	s_nop 0
	global_load_lds_dwordx4 v[188:189], off
	s_mov_b64 s[12:13], 0x3c0080
	v_lshl_add_u64 v[188:189], v[92:93], 0, s[12:13]
	s_add_u32 m0, s98, 0xb000
	s_nop 0
	global_load_lds_dwordx4 v[188:189], off
	s_cmp_eq_u64 s[4:5], 0
	s_cbranch_scc1 .Lg160o_q
.Lg160o_p:
	v_add_u32_e32 v164, s9, v97
	v_add_u32_e32 v165, s9, v99
	v_add_u32_e32 v192, v164, v101
	v_add_u32_e32 v196, v165, v101
	v_add_u32_e32 v164, v164, v100
	v_add_u32_e32 v165, v165, v100
	s_waitcnt vmcnt(7) lgkmcnt(0)
	s_barrier
	ds_read_b128 v[152:155], v164 offset:20480
	ds_read_b128 v[156:159], v164 offset:22528
	ds_read_b128 v[108:111], v165
	ds_read_b128 v[112:115], v165 offset:2048
	ds_read_b128 v[116:119], v165 offset:4096
	ds_read_b128 v[120:123], v165 offset:6144
	ds_read_b128 v[124:127], v165 offset:8192
	ds_read_b128 v[132:135], v165 offset:10240
	ds_read_b128 v[136:139], v165 offset:12288
	ds_read_b128 v[140:143], v165 offset:14336
	ds_read_b128 v[144:147], v165 offset:16384
	ds_read_b128 v[148:151], v165 offset:18432
	s_waitcnt lgkmcnt(9)
	v_mfma_f32_16x16x32_bf16 v[76:79], v[152:155], v[108:111], v[76:79]
	v_mfma_f32_16x16x32_bf16 v[72:75], v[156:159], v[108:111], v[72:75]
	ds_read_b128 v[200:203], v192 offset:20480
	s_waitcnt lgkmcnt(9)
	v_mfma_f32_16x16x32_bf16 v[68:71], v[152:155], v[112:115], v[68:71]
	v_mfma_f32_16x16x32_bf16 v[64:67], v[156:159], v[112:115], v[64:67]
	ds_read_b128 v[204:207], v192 offset:22528
	s_waitcnt lgkmcnt(9)
	v_mfma_f32_16x16x32_bf16 v[60:63], v[152:155], v[116:119], v[60:63]
	v_mfma_f32_16x16x32_bf16 v[56:59], v[156:159], v[116:119], v[56:59]
	ds_read_b128 v[160:163], v196
	s_waitcnt lgkmcnt(9)
	v_mfma_f32_16x16x32_bf16 v[52:55], v[152:155], v[120:123], v[52:55]
	v_mfma_f32_16x16x32_bf16 v[48:51], v[156:159], v[120:123], v[48:51]
	ds_read_b128 v[164:167], v196 offset:2048
	s_waitcnt lgkmcnt(9)
	v_mfma_f32_16x16x32_bf16 v[44:47], v[152:155], v[124:127], v[44:47]
	v_mfma_f32_16x16x32_bf16 v[40:43], v[156:159], v[124:127], v[40:43]
	ds_read_b128 v[168:171], v196 offset:4096
	s_waitcnt lgkmcnt(9)
	v_mfma_f32_16x16x32_bf16 v[36:39], v[152:155], v[132:135], v[36:39]
	v_mfma_f32_16x16x32_bf16 v[32:35], v[156:159], v[132:135], v[32:35]
	ds_read_b128 v[172:175], v196 offset:6144
	s_waitcnt lgkmcnt(9)
	v_mfma_f32_16x16x32_bf16 v[28:31], v[152:155], v[136:139], v[28:31]
	v_mfma_f32_16x16x32_bf16 v[24:27], v[156:159], v[136:139], v[24:27]
	ds_read_b128 v[176:179], v196 offset:8192
	s_waitcnt lgkmcnt(9)
	v_mfma_f32_16x16x32_bf16 v[20:23], v[152:155], v[140:143], v[20:23]
	v_mfma_f32_16x16x32_bf16 v[16:19], v[156:159], v[140:143], v[16:19]
	ds_read_b128 v[180:183], v196 offset:10240
	s_waitcnt lgkmcnt(9)
	v_mfma_f32_16x16x32_bf16 v[12:15], v[152:155], v[144:147], v[12:15]
	v_mfma_f32_16x16x32_bf16 v[8:11], v[156:159], v[144:147], v[8:11]
	ds_read_b128 v[184:187], v196 offset:12288
	s_waitcnt lgkmcnt(9)
	v_mfma_f32_16x16x32_bf16 v[4:7], v[152:155], v[148:151], v[4:7]
	v_mfma_f32_16x16x32_bf16 v[0:3], v[156:159], v[148:151], v[0:3]
	ds_read_b128 v[188:191], v196 offset:14336
	ds_read_b128 v[192:195], v196 offset:16384
	ds_read_b128 v[196:199], v196 offset:18432
	s_waitcnt lgkmcnt(9)
	v_mfma_f32_16x16x32_bf16 v[76:79], v[200:203], v[160:163], v[76:79]
	v_mfma_f32_16x16x32_bf16 v[72:75], v[204:207], v[160:163], v[72:75]
	s_waitcnt lgkmcnt(8)
	v_mfma_f32_16x16x32_bf16 v[68:71], v[200:203], v[164:167], v[68:71]
	v_mfma_f32_16x16x32_bf16 v[64:67], v[204:207], v[164:167], v[64:67]
	s_waitcnt lgkmcnt(7)
	v_mfma_f32_16x16x32_bf16 v[60:63], v[200:203], v[168:171], v[60:63]
	v_mfma_f32_16x16x32_bf16 v[56:59], v[204:207], v[168:171], v[56:59]
	s_waitcnt lgkmcnt(6)
	v_mfma_f32_16x16x32_bf16 v[52:55], v[200:203], v[172:175], v[52:55]
	v_mfma_f32_16x16x32_bf16 v[48:51], v[204:207], v[172:175], v[48:51]
	s_waitcnt lgkmcnt(5)
	v_mfma_f32_16x16x32_bf16 v[44:47], v[200:203], v[176:179], v[44:47]
	v_mfma_f32_16x16x32_bf16 v[40:43], v[204:207], v[176:179], v[40:43]
	s_waitcnt lgkmcnt(4)
	v_mfma_f32_16x16x32_bf16 v[36:39], v[200:203], v[180:183], v[36:39]
	v_mfma_f32_16x16x32_bf16 v[32:35], v[204:207], v[180:183], v[32:35]
	s_waitcnt lgkmcnt(3)
	v_mfma_f32_16x16x32_bf16 v[28:31], v[200:203], v[184:187], v[28:31]
	v_mfma_f32_16x16x32_bf16 v[24:27], v[204:207], v[184:187], v[24:27]
	s_waitcnt lgkmcnt(2)
	v_mfma_f32_16x16x32_bf16 v[20:23], v[200:203], v[188:191], v[20:23]
	v_mfma_f32_16x16x32_bf16 v[16:19], v[204:207], v[188:191], v[16:19]
	s_waitcnt lgkmcnt(1)
	v_mfma_f32_16x16x32_bf16 v[12:15], v[200:203], v[192:195], v[12:15]
	v_mfma_f32_16x16x32_bf16 v[8:11], v[204:207], v[192:195], v[8:11]
	s_waitcnt lgkmcnt(0)
	v_mfma_f32_16x16x32_bf16 v[4:7], v[200:203], v[196:199], v[4:7]
	v_mfma_f32_16x16x32_bf16 v[0:3], v[204:207], v[196:199], v[0:3]
	s_add_u32 s12, s9, 0x1a000
	s_cmp_ge_u32 s12, 0x27000
	s_cselect_b32 s13, 0x27000, 0
	s_sub_u32 s12, s12, s13
	v_add_u32_e32 v168, s12, v98
	s_add_u32 s12, s10, 0x80
	s_addc_u32 s13, s11, 0
	v_lshl_add_u64 v[94:95], v[90:91], 0, s[12:13]
	v_lshl_add_u64 v[186:187], v[92:93], 0, s[12:13]
	v_readfirstlane_b32 s98, v168
	v_lshl_add_u64 v[188:189], v[94:95], 0, s[78:79]
	s_mov_b32 m0, s98
	s_nop 0
	global_load_lds_dwordx4 v[188:189], off
	v_lshl_add_u64 v[188:189], v[94:95], 0, s[80:81]
	s_add_u32 m0, s98, 0x2000
	s_nop 0
	global_load_lds_dwordx4 v[188:189], off
	v_lshl_add_u64 v[188:189], v[94:95], 0, s[82:83]
	s_add_u32 m0, s98, 0x4000
	s_nop 0
	global_load_lds_dwordx4 v[188:189], off
	s_mov_b64 s[12:13], 0x360080
	v_lshl_add_u64 v[188:189], v[186:187], 0, s[12:13]
	s_add_u32 m0, s98, 0x5000
	s_nop 0
	global_load_lds_dwordx4 v[188:189], off
	s_mov_b64 s[12:13], 0x380080
	v_lshl_add_u64 v[188:189], v[186:187], 0, s[12:13]
	s_add_u32 m0, s98, 0x7000
	s_nop 0
	global_load_lds_dwordx4 v[188:189], off
	s_mov_b64 s[12:13], 0x3a0080
	v_lshl_add_u64 v[188:189], v[186:187], 0, s[12:13]
	s_add_u32 m0, s98, 0x9000
	s_nop 0
	global_load_lds_dwordx4 v[188:189], off
	s_mov_b64 s[12:13], 0x3c0080
	v_lshl_add_u64 v[188:189], v[186:187], 0, s[12:13]
	s_add_u32 m0, s98, 0xb000
	s_nop 0
	global_load_lds_dwordx4 v[188:189], off
	s_add_u32 s9, s9, 0xd000
	s_cmp_eq_u32 s9, 0x27000
	s_cselect_b32 s9, 0, s9
	s_add_u32 s10, s10, 0x80
	s_addc_u32 s11, s11, 0
	s_cmpk_eq_i32 s10, 0x700
	s_cbranch_scc0 .Lg160o_p
	v_add_u32_e32 v164, s9, v97
	v_add_u32_e32 v165, s9, v99
	v_add_u32_e32 v192, v164, v101
	v_add_u32_e32 v196, v165, v101
	v_add_u32_e32 v164, v164, v100
	v_add_u32_e32 v165, v165, v100
	s_waitcnt vmcnt(7) lgkmcnt(0)
	s_barrier
	ds_read_b128 v[152:155], v164 offset:20480
	ds_read_b128 v[156:159], v164 offset:22528
	ds_read_b128 v[108:111], v165
	ds_read_b128 v[112:115], v165 offset:2048
	ds_read_b128 v[116:119], v165 offset:4096
	ds_read_b128 v[120:123], v165 offset:6144
	ds_read_b128 v[124:127], v165 offset:8192
	ds_read_b128 v[132:135], v165 offset:10240
	ds_read_b128 v[136:139], v165 offset:12288
	ds_read_b128 v[140:143], v165 offset:14336
	ds_read_b128 v[144:147], v165 offset:16384
	ds_read_b128 v[148:151], v165 offset:18432
	s_waitcnt lgkmcnt(9)
	v_mfma_f32_16x16x32_bf16 v[76:79], v[152:155], v[108:111], v[76:79]
	v_mfma_f32_16x16x32_bf16 v[72:75], v[156:159], v[108:111], v[72:75]
	ds_read_b128 v[200:203], v192 offset:20480
	s_waitcnt lgkmcnt(9)
	v_mfma_f32_16x16x32_bf16 v[68:71], v[152:155], v[112:115], v[68:71]
	v_mfma_f32_16x16x32_bf16 v[64:67], v[156:159], v[112:115], v[64:67]
	ds_read_b128 v[204:207], v192 offset:22528
	s_waitcnt lgkmcnt(9)
	v_mfma_f32_16x16x32_bf16 v[60:63], v[152:155], v[116:119], v[60:63]
	v_mfma_f32_16x16x32_bf16 v[56:59], v[156:159], v[116:119], v[56:59]
	ds_read_b128 v[160:163], v196
	s_waitcnt lgkmcnt(9)
	v_mfma_f32_16x16x32_bf16 v[52:55], v[152:155], v[120:123], v[52:55]
	v_mfma_f32_16x16x32_bf16 v[48:51], v[156:159], v[120:123], v[48:51]
	ds_read_b128 v[164:167], v196 offset:2048
	s_waitcnt lgkmcnt(9)
	v_mfma_f32_16x16x32_bf16 v[44:47], v[152:155], v[124:127], v[44:47]
	v_mfma_f32_16x16x32_bf16 v[40:43], v[156:159], v[124:127], v[40:43]
	ds_read_b128 v[168:171], v196 offset:4096
	s_waitcnt lgkmcnt(9)
	v_mfma_f32_16x16x32_bf16 v[36:39], v[152:155], v[132:135], v[36:39]
	v_mfma_f32_16x16x32_bf16 v[32:35], v[156:159], v[132:135], v[32:35]
	ds_read_b128 v[172:175], v196 offset:6144
	s_waitcnt lgkmcnt(9)
	v_mfma_f32_16x16x32_bf16 v[28:31], v[152:155], v[136:139], v[28:31]
	v_mfma_f32_16x16x32_bf16 v[24:27], v[156:159], v[136:139], v[24:27]
	ds_read_b128 v[176:179], v196 offset:8192
	s_waitcnt lgkmcnt(9)
	v_mfma_f32_16x16x32_bf16 v[20:23], v[152:155], v[140:143], v[20:23]
	v_mfma_f32_16x16x32_bf16 v[16:19], v[156:159], v[140:143], v[16:19]
	ds_read_b128 v[180:183], v196 offset:10240
	s_waitcnt lgkmcnt(9)
	v_mfma_f32_16x16x32_bf16 v[12:15], v[152:155], v[144:147], v[12:15]
	v_mfma_f32_16x16x32_bf16 v[8:11], v[156:159], v[144:147], v[8:11]
	ds_read_b128 v[184:187], v196 offset:12288
	s_waitcnt lgkmcnt(9)
	v_mfma_f32_16x16x32_bf16 v[4:7], v[152:155], v[148:151], v[4:7]
	v_mfma_f32_16x16x32_bf16 v[0:3], v[156:159], v[148:151], v[0:3]
	ds_read_b128 v[188:191], v196 offset:14336
	ds_read_b128 v[192:195], v196 offset:16384
	ds_read_b128 v[196:199], v196 offset:18432
	s_waitcnt lgkmcnt(9)
	v_mfma_f32_16x16x32_bf16 v[76:79], v[200:203], v[160:163], v[76:79]
	v_mfma_f32_16x16x32_bf16 v[72:75], v[204:207], v[160:163], v[72:75]
	s_waitcnt lgkmcnt(8)
	v_mfma_f32_16x16x32_bf16 v[68:71], v[200:203], v[164:167], v[68:71]
	v_mfma_f32_16x16x32_bf16 v[64:67], v[204:207], v[164:167], v[64:67]
	s_waitcnt lgkmcnt(7)
	v_mfma_f32_16x16x32_bf16 v[60:63], v[200:203], v[168:171], v[60:63]
	v_mfma_f32_16x16x32_bf16 v[56:59], v[204:207], v[168:171], v[56:59]
	s_waitcnt lgkmcnt(6)
	v_mfma_f32_16x16x32_bf16 v[52:55], v[200:203], v[172:175], v[52:55]
	v_mfma_f32_16x16x32_bf16 v[48:51], v[204:207], v[172:175], v[48:51]
	s_waitcnt lgkmcnt(5)
	v_mfma_f32_16x16x32_bf16 v[44:47], v[200:203], v[176:179], v[44:47]
	v_mfma_f32_16x16x32_bf16 v[40:43], v[204:207], v[176:179], v[40:43]
	s_waitcnt lgkmcnt(4)
	v_mfma_f32_16x16x32_bf16 v[36:39], v[200:203], v[180:183], v[36:39]
	v_mfma_f32_16x16x32_bf16 v[32:35], v[204:207], v[180:183], v[32:35]
	s_waitcnt lgkmcnt(3)
	v_mfma_f32_16x16x32_bf16 v[28:31], v[200:203], v[184:187], v[28:31]
	v_mfma_f32_16x16x32_bf16 v[24:27], v[204:207], v[184:187], v[24:27]
	s_waitcnt lgkmcnt(2)
	v_mfma_f32_16x16x32_bf16 v[20:23], v[200:203], v[188:191], v[20:23]
	v_mfma_f32_16x16x32_bf16 v[16:19], v[204:207], v[188:191], v[16:19]
	s_waitcnt lgkmcnt(1)
	v_mfma_f32_16x16x32_bf16 v[12:15], v[200:203], v[192:195], v[12:15]
	v_mfma_f32_16x16x32_bf16 v[8:11], v[204:207], v[192:195], v[8:11]
	s_waitcnt lgkmcnt(0)
	v_mfma_f32_16x16x32_bf16 v[4:7], v[200:203], v[196:199], v[4:7]
	v_mfma_f32_16x16x32_bf16 v[0:3], v[204:207], v[196:199], v[0:3]
	s_add_u32 s9, s9, 0xd000
	s_cmp_eq_u32 s9, 0x27000
	s_cselect_b32 s9, 0, s9
	v_add_u32_e32 v164, s9, v97
	v_add_u32_e32 v165, s9, v99
	v_add_u32_e32 v192, v164, v101
	v_add_u32_e32 v196, v165, v101
	v_add_u32_e32 v164, v164, v100
	v_add_u32_e32 v165, v165, v100
	s_waitcnt vmcnt(0) lgkmcnt(0)
	s_barrier
	ds_read_b128 v[152:155], v164 offset:20480
	ds_read_b128 v[156:159], v164 offset:22528
	ds_read_b128 v[108:111], v165
	ds_read_b128 v[112:115], v165 offset:2048
	ds_read_b128 v[116:119], v165 offset:4096
	ds_read_b128 v[120:123], v165 offset:6144
	ds_read_b128 v[124:127], v165 offset:8192
	ds_read_b128 v[132:135], v165 offset:10240
	ds_read_b128 v[136:139], v165 offset:12288
	ds_read_b128 v[140:143], v165 offset:14336
	ds_read_b128 v[144:147], v165 offset:16384
	ds_read_b128 v[148:151], v165 offset:18432
	s_waitcnt lgkmcnt(9)
	v_mfma_f32_16x16x32_bf16 v[76:79], v[152:155], v[108:111], v[76:79]
	v_mfma_f32_16x16x32_bf16 v[72:75], v[156:159], v[108:111], v[72:75]
	ds_read_b128 v[200:203], v192 offset:20480
	s_waitcnt lgkmcnt(9)
	v_mfma_f32_16x16x32_bf16 v[68:71], v[152:155], v[112:115], v[68:71]
	v_mfma_f32_16x16x32_bf16 v[64:67], v[156:159], v[112:115], v[64:67]
	ds_read_b128 v[204:207], v192 offset:22528
	s_waitcnt lgkmcnt(9)
	v_mfma_f32_16x16x32_bf16 v[60:63], v[152:155], v[116:119], v[60:63]
	v_mfma_f32_16x16x32_bf16 v[56:59], v[156:159], v[116:119], v[56:59]
	ds_read_b128 v[160:163], v196
	s_waitcnt lgkmcnt(9)
	v_mfma_f32_16x16x32_bf16 v[52:55], v[152:155], v[120:123], v[52:55]
	v_mfma_f32_16x16x32_bf16 v[48:51], v[156:159], v[120:123], v[48:51]
	ds_read_b128 v[164:167], v196 offset:2048
	s_waitcnt lgkmcnt(9)
	v_mfma_f32_16x16x32_bf16 v[44:47], v[152:155], v[124:127], v[44:47]
	v_mfma_f32_16x16x32_bf16 v[40:43], v[156:159], v[124:127], v[40:43]
	ds_read_b128 v[168:171], v196 offset:4096
	s_waitcnt lgkmcnt(9)
	v_mfma_f32_16x16x32_bf16 v[36:39], v[152:155], v[132:135], v[36:39]
	v_mfma_f32_16x16x32_bf16 v[32:35], v[156:159], v[132:135], v[32:35]
	ds_read_b128 v[172:175], v196 offset:6144
	s_waitcnt lgkmcnt(9)
	v_mfma_f32_16x16x32_bf16 v[28:31], v[152:155], v[136:139], v[28:31]
	v_mfma_f32_16x16x32_bf16 v[24:27], v[156:159], v[136:139], v[24:27]
	ds_read_b128 v[176:179], v196 offset:8192
	s_waitcnt lgkmcnt(9)
	v_mfma_f32_16x16x32_bf16 v[20:23], v[152:155], v[140:143], v[20:23]
	v_mfma_f32_16x16x32_bf16 v[16:19], v[156:159], v[140:143], v[16:19]
	ds_read_b128 v[180:183], v196 offset:10240
	s_waitcnt lgkmcnt(9)
	v_mfma_f32_16x16x32_bf16 v[12:15], v[152:155], v[144:147], v[12:15]
	v_mfma_f32_16x16x32_bf16 v[8:11], v[156:159], v[144:147], v[8:11]
	ds_read_b128 v[184:187], v196 offset:12288
	s_waitcnt lgkmcnt(9)
	v_mfma_f32_16x16x32_bf16 v[4:7], v[152:155], v[148:151], v[4:7]
	v_mfma_f32_16x16x32_bf16 v[0:3], v[156:159], v[148:151], v[0:3]
	ds_read_b128 v[188:191], v196 offset:14336
	ds_read_b128 v[192:195], v196 offset:16384
	ds_read_b128 v[196:199], v196 offset:18432
	s_waitcnt lgkmcnt(9)
	v_mfma_f32_16x16x32_bf16 v[76:79], v[200:203], v[160:163], v[76:79]
	v_mfma_f32_16x16x32_bf16 v[72:75], v[204:207], v[160:163], v[72:75]
	s_waitcnt lgkmcnt(8)
	v_mfma_f32_16x16x32_bf16 v[68:71], v[200:203], v[164:167], v[68:71]
	v_mfma_f32_16x16x32_bf16 v[64:67], v[204:207], v[164:167], v[64:67]
	s_waitcnt lgkmcnt(7)
	v_mfma_f32_16x16x32_bf16 v[60:63], v[200:203], v[168:171], v[60:63]
	v_mfma_f32_16x16x32_bf16 v[56:59], v[204:207], v[168:171], v[56:59]
	s_waitcnt lgkmcnt(6)
	v_mfma_f32_16x16x32_bf16 v[52:55], v[200:203], v[172:175], v[52:55]
	v_mfma_f32_16x16x32_bf16 v[48:51], v[204:207], v[172:175], v[48:51]
	s_waitcnt lgkmcnt(5)
	v_mfma_f32_16x16x32_bf16 v[44:47], v[200:203], v[176:179], v[44:47]
	v_mfma_f32_16x16x32_bf16 v[40:43], v[204:207], v[176:179], v[40:43]
	s_waitcnt lgkmcnt(4)
	v_mfma_f32_16x16x32_bf16 v[36:39], v[200:203], v[180:183], v[36:39]
	v_mfma_f32_16x16x32_bf16 v[32:35], v[204:207], v[180:183], v[32:35]
	s_waitcnt lgkmcnt(3)
	v_mfma_f32_16x16x32_bf16 v[28:31], v[200:203], v[184:187], v[28:31]
	v_mfma_f32_16x16x32_bf16 v[24:27], v[204:207], v[184:187], v[24:27]
	s_waitcnt lgkmcnt(2)
	v_mfma_f32_16x16x32_bf16 v[20:23], v[200:203], v[188:191], v[20:23]
	v_mfma_f32_16x16x32_bf16 v[16:19], v[204:207], v[188:191], v[16:19]
	s_waitcnt lgkmcnt(1)
	v_mfma_f32_16x16x32_bf16 v[12:15], v[200:203], v[192:195], v[12:15]
	v_mfma_f32_16x16x32_bf16 v[8:11], v[204:207], v[192:195], v[8:11]
	s_waitcnt lgkmcnt(0)
	v_mfma_f32_16x16x32_bf16 v[4:7], v[200:203], v[196:199], v[4:7]
	v_mfma_f32_16x16x32_bf16 v[0:3], v[204:207], v[196:199], v[0:3]
	s_add_u32 s9, s9, 0xd000
	s_cmp_eq_u32 s9, 0x27000
	s_cselect_b32 s9, 0, s9
	s_branch .Lg160o_epi
.Lg160o_q:
	s_add_u32 s12, s9, 0x1a000
	s_cmp_ge_u32 s12, 0x27000
	s_cselect_b32 s13, 0x27000, 0
	s_sub_u32 s12, s12, s13
	v_add_u32_e32 v168, s12, v98
	s_add_u32 s12, s10, 0x80
	s_addc_u32 s13, s11, 0
	v_lshl_add_u64 v[94:95], v[90:91], 0, s[12:13]
	v_lshl_add_u64 v[186:187], v[92:93], 0, s[12:13]
	v_readfirstlane_b32 s98, v168
	v_add_u32_e32 v164, s9, v97
	v_add_u32_e32 v165, s9, v99
	v_add_u32_e32 v192, v164, v101
	v_add_u32_e32 v196, v165, v101
	v_add_u32_e32 v164, v164, v100
	v_add_u32_e32 v165, v165, v100
	s_waitcnt vmcnt(6) lgkmcnt(0)
	s_barrier
	v_lshl_add_u64 v[188:189], v[94:95], 0, s[78:79]
	s_mov_b32 m0, s98
	s_nop 0
	global_load_lds_dwordx4 v[188:189], off
	v_lshl_add_u64 v[188:189], v[94:95], 0, s[80:81]
	s_add_u32 m0, s98, 0x2000
	s_nop 0
	global_load_lds_dwordx4 v[188:189], off
	s_mov_b64 s[12:13], 0x360080
	v_lshl_add_u64 v[188:189], v[186:187], 0, s[12:13]
	s_add_u32 m0, s98, 0x5000
	s_nop 0
	global_load_lds_dwordx4 v[188:189], off
	s_mov_b64 s[12:13], 0x380080
	v_lshl_add_u64 v[188:189], v[186:187], 0, s[12:13]
	s_add_u32 m0, s98, 0x7000
	s_nop 0
	global_load_lds_dwordx4 v[188:189], off
	s_mov_b64 s[12:13], 0x3a0080
	v_lshl_add_u64 v[188:189], v[186:187], 0, s[12:13]
	s_add_u32 m0, s98, 0x9000
	s_nop 0
	global_load_lds_dwordx4 v[188:189], off
	s_mov_b64 s[12:13], 0x3c0080
	v_lshl_add_u64 v[188:189], v[186:187], 0, s[12:13]
	s_add_u32 m0, s98, 0xb000
	s_nop 0
	global_load_lds_dwordx4 v[188:189], off
	ds_read_b128 v[152:155], v164 offset:20480
	ds_read_b128 v[156:159], v164 offset:22528
	ds_read_b128 v[108:111], v165
	ds_read_b128 v[112:115], v165 offset:2048
	ds_read_b128 v[116:119], v165 offset:4096
	ds_read_b128 v[120:123], v165 offset:6144
	ds_read_b128 v[124:127], v165 offset:8192
	ds_read_b128 v[132:135], v165 offset:10240
	ds_read_b128 v[136:139], v165 offset:12288
	ds_read_b128 v[140:143], v165 offset:14336
	ds_read_b128 v[144:147], v165 offset:16384
	ds_read_b128 v[148:151], v165 offset:18432
	s_waitcnt lgkmcnt(9)
	v_mfma_f32_16x16x32_bf16 v[76:79], v[152:155], v[108:111], v[76:79]
	v_mfma_f32_16x16x32_bf16 v[72:75], v[156:159], v[108:111], v[72:75]
	ds_read_b128 v[200:203], v192 offset:20480
	s_waitcnt lgkmcnt(9)
	v_mfma_f32_16x16x32_bf16 v[68:71], v[152:155], v[112:115], v[68:71]
	v_mfma_f32_16x16x32_bf16 v[64:67], v[156:159], v[112:115], v[64:67]
	ds_read_b128 v[204:207], v192 offset:22528
	s_waitcnt lgkmcnt(9)
	v_mfma_f32_16x16x32_bf16 v[60:63], v[152:155], v[116:119], v[60:63]
	v_mfma_f32_16x16x32_bf16 v[56:59], v[156:159], v[116:119], v[56:59]
	ds_read_b128 v[160:163], v196
	s_waitcnt lgkmcnt(9)
	v_mfma_f32_16x16x32_bf16 v[52:55], v[152:155], v[120:123], v[52:55]
	v_mfma_f32_16x16x32_bf16 v[48:51], v[156:159], v[120:123], v[48:51]
	ds_read_b128 v[164:167], v196 offset:2048
	s_waitcnt lgkmcnt(9)
	v_mfma_f32_16x16x32_bf16 v[44:47], v[152:155], v[124:127], v[44:47]
	v_mfma_f32_16x16x32_bf16 v[40:43], v[156:159], v[124:127], v[40:43]
	ds_read_b128 v[168:171], v196 offset:4096
	s_waitcnt lgkmcnt(9)
	v_mfma_f32_16x16x32_bf16 v[36:39], v[152:155], v[132:135], v[36:39]
	v_mfma_f32_16x16x32_bf16 v[32:35], v[156:159], v[132:135], v[32:35]
	ds_read_b128 v[172:175], v196 offset:6144
	s_waitcnt lgkmcnt(9)
	v_mfma_f32_16x16x32_bf16 v[28:31], v[152:155], v[136:139], v[28:31]
	v_mfma_f32_16x16x32_bf16 v[24:27], v[156:159], v[136:139], v[24:27]
	ds_read_b128 v[176:179], v196 offset:8192
	s_waitcnt lgkmcnt(9)
	v_mfma_f32_16x16x32_bf16 v[20:23], v[152:155], v[140:143], v[20:23]
	v_mfma_f32_16x16x32_bf16 v[16:19], v[156:159], v[140:143], v[16:19]
	ds_read_b128 v[180:183], v196 offset:10240
	s_waitcnt lgkmcnt(9)
	v_mfma_f32_16x16x32_bf16 v[12:15], v[152:155], v[144:147], v[12:15]
	v_mfma_f32_16x16x32_bf16 v[8:11], v[156:159], v[144:147], v[8:11]
	ds_read_b128 v[184:187], v196 offset:12288
	s_waitcnt lgkmcnt(9)
	v_mfma_f32_16x16x32_bf16 v[4:7], v[152:155], v[148:151], v[4:7]
	v_mfma_f32_16x16x32_bf16 v[0:3], v[156:159], v[148:151], v[0:3]
	ds_read_b128 v[188:191], v196 offset:14336
	ds_read_b128 v[192:195], v196 offset:16384
	ds_read_b128 v[196:199], v196 offset:18432
	s_waitcnt lgkmcnt(9)
	v_mfma_f32_16x16x32_bf16 v[76:79], v[200:203], v[160:163], v[76:79]
	v_mfma_f32_16x16x32_bf16 v[72:75], v[204:207], v[160:163], v[72:75]
	s_waitcnt lgkmcnt(8)
	v_mfma_f32_16x16x32_bf16 v[68:71], v[200:203], v[164:167], v[68:71]
	v_mfma_f32_16x16x32_bf16 v[64:67], v[204:207], v[164:167], v[64:67]
	s_waitcnt lgkmcnt(7)
	v_mfma_f32_16x16x32_bf16 v[60:63], v[200:203], v[168:171], v[60:63]
	v_mfma_f32_16x16x32_bf16 v[56:59], v[204:207], v[168:171], v[56:59]
	s_waitcnt lgkmcnt(6)
	v_mfma_f32_16x16x32_bf16 v[52:55], v[200:203], v[172:175], v[52:55]
	v_mfma_f32_16x16x32_bf16 v[48:51], v[204:207], v[172:175], v[48:51]
	s_waitcnt lgkmcnt(5)
	v_mfma_f32_16x16x32_bf16 v[44:47], v[200:203], v[176:179], v[44:47]
	v_mfma_f32_16x16x32_bf16 v[40:43], v[204:207], v[176:179], v[40:43]
	s_waitcnt lgkmcnt(4)
	v_mfma_f32_16x16x32_bf16 v[36:39], v[200:203], v[180:183], v[36:39]
	v_mfma_f32_16x16x32_bf16 v[32:35], v[204:207], v[180:183], v[32:35]
	s_waitcnt lgkmcnt(3)
	v_mfma_f32_16x16x32_bf16 v[28:31], v[200:203], v[184:187], v[28:31]
	v_mfma_f32_16x16x32_bf16 v[24:27], v[204:207], v[184:187], v[24:27]
	s_waitcnt lgkmcnt(2)
	v_mfma_f32_16x16x32_bf16 v[20:23], v[200:203], v[188:191], v[20:23]
	v_mfma_f32_16x16x32_bf16 v[16:19], v[204:207], v[188:191], v[16:19]
	s_waitcnt lgkmcnt(1)
	v_mfma_f32_16x16x32_bf16 v[12:15], v[200:203], v[192:195], v[12:15]
	v_mfma_f32_16x16x32_bf16 v[8:11], v[204:207], v[192:195], v[8:11]
	s_waitcnt lgkmcnt(0)
	v_mfma_f32_16x16x32_bf16 v[4:7], v[200:203], v[196:199], v[4:7]
	v_mfma_f32_16x16x32_bf16 v[0:3], v[204:207], v[196:199], v[0:3]
	s_add_u32 s9, s9, 0xd000
	s_cmp_eq_u32 s9, 0x27000
	s_cselect_b32 s9, 0, s9
	s_add_u32 s10, s10, 0x80
	s_addc_u32 s11, s11, 0
	s_cmpk_eq_i32 s10, 0x700
	s_cbranch_scc0 .Lg160o_q
	v_add_u32_e32 v164, s9, v97
	v_add_u32_e32 v165, s9, v99
	v_add_u32_e32 v192, v164, v101
	v_add_u32_e32 v196, v165, v101
	v_add_u32_e32 v164, v164, v100
	v_add_u32_e32 v165, v165, v100
	s_waitcnt vmcnt(6) lgkmcnt(0)
	s_barrier
	ds_read_b128 v[152:155], v164 offset:20480
	ds_read_b128 v[156:159], v164 offset:22528
	ds_read_b128 v[108:111], v165
	ds_read_b128 v[112:115], v165 offset:2048
	ds_read_b128 v[116:119], v165 offset:4096
	ds_read_b128 v[120:123], v165 offset:6144
	ds_read_b128 v[124:127], v165 offset:8192
	ds_read_b128 v[132:135], v165 offset:10240
	ds_read_b128 v[136:139], v165 offset:12288
	ds_read_b128 v[140:143], v165 offset:14336
	ds_read_b128 v[144:147], v165 offset:16384
	ds_read_b128 v[148:151], v165 offset:18432
	s_waitcnt lgkmcnt(9)
	v_mfma_f32_16x16x32_bf16 v[76:79], v[152:155], v[108:111], v[76:79]
	v_mfma_f32_16x16x32_bf16 v[72:75], v[156:159], v[108:111], v[72:75]
	ds_read_b128 v[200:203], v192 offset:20480
	s_waitcnt lgkmcnt(9)
	v_mfma_f32_16x16x32_bf16 v[68:71], v[152:155], v[112:115], v[68:71]
	v_mfma_f32_16x16x32_bf16 v[64:67], v[156:159], v[112:115], v[64:67]
	ds_read_b128 v[204:207], v192 offset:22528
	s_waitcnt lgkmcnt(9)
	v_mfma_f32_16x16x32_bf16 v[60:63], v[152:155], v[116:119], v[60:63]
	v_mfma_f32_16x16x32_bf16 v[56:59], v[156:159], v[116:119], v[56:59]
	ds_read_b128 v[160:163], v196
	s_waitcnt lgkmcnt(9)
	v_mfma_f32_16x16x32_bf16 v[52:55], v[152:155], v[120:123], v[52:55]
	v_mfma_f32_16x16x32_bf16 v[48:51], v[156:159], v[120:123], v[48:51]
	ds_read_b128 v[164:167], v196 offset:2048
	s_waitcnt lgkmcnt(9)
	v_mfma_f32_16x16x32_bf16 v[44:47], v[152:155], v[124:127], v[44:47]
	v_mfma_f32_16x16x32_bf16 v[40:43], v[156:159], v[124:127], v[40:43]
	ds_read_b128 v[168:171], v196 offset:4096
	s_waitcnt lgkmcnt(9)
	v_mfma_f32_16x16x32_bf16 v[36:39], v[152:155], v[132:135], v[36:39]
	v_mfma_f32_16x16x32_bf16 v[32:35], v[156:159], v[132:135], v[32:35]
	ds_read_b128 v[172:175], v196 offset:6144
	s_waitcnt lgkmcnt(9)
	v_mfma_f32_16x16x32_bf16 v[28:31], v[152:155], v[136:139], v[28:31]
	v_mfma_f32_16x16x32_bf16 v[24:27], v[156:159], v[136:139], v[24:27]
	ds_read_b128 v[176:179], v196 offset:8192
	s_waitcnt lgkmcnt(9)
	v_mfma_f32_16x16x32_bf16 v[20:23], v[152:155], v[140:143], v[20:23]
	v_mfma_f32_16x16x32_bf16 v[16:19], v[156:159], v[140:143], v[16:19]
	ds_read_b128 v[180:183], v196 offset:10240
	s_waitcnt lgkmcnt(9)
	v_mfma_f32_16x16x32_bf16 v[12:15], v[152:155], v[144:147], v[12:15]
	v_mfma_f32_16x16x32_bf16 v[8:11], v[156:159], v[144:147], v[8:11]
	ds_read_b128 v[184:187], v196 offset:12288
	s_waitcnt lgkmcnt(9)
	v_mfma_f32_16x16x32_bf16 v[4:7], v[152:155], v[148:151], v[4:7]
	v_mfma_f32_16x16x32_bf16 v[0:3], v[156:159], v[148:151], v[0:3]
	ds_read_b128 v[188:191], v196 offset:14336
	ds_read_b128 v[192:195], v196 offset:16384
	ds_read_b128 v[196:199], v196 offset:18432
	s_waitcnt lgkmcnt(9)
	v_mfma_f32_16x16x32_bf16 v[76:79], v[200:203], v[160:163], v[76:79]
	v_mfma_f32_16x16x32_bf16 v[72:75], v[204:207], v[160:163], v[72:75]
	s_waitcnt lgkmcnt(8)
	v_mfma_f32_16x16x32_bf16 v[68:71], v[200:203], v[164:167], v[68:71]
	v_mfma_f32_16x16x32_bf16 v[64:67], v[204:207], v[164:167], v[64:67]
	s_waitcnt lgkmcnt(7)
	v_mfma_f32_16x16x32_bf16 v[60:63], v[200:203], v[168:171], v[60:63]
	v_mfma_f32_16x16x32_bf16 v[56:59], v[204:207], v[168:171], v[56:59]
	s_waitcnt lgkmcnt(6)
	v_mfma_f32_16x16x32_bf16 v[52:55], v[200:203], v[172:175], v[52:55]
	v_mfma_f32_16x16x32_bf16 v[48:51], v[204:207], v[172:175], v[48:51]
	s_waitcnt lgkmcnt(5)
	v_mfma_f32_16x16x32_bf16 v[44:47], v[200:203], v[176:179], v[44:47]
	v_mfma_f32_16x16x32_bf16 v[40:43], v[204:207], v[176:179], v[40:43]
	s_waitcnt lgkmcnt(4)
	v_mfma_f32_16x16x32_bf16 v[36:39], v[200:203], v[180:183], v[36:39]
	v_mfma_f32_16x16x32_bf16 v[32:35], v[204:207], v[180:183], v[32:35]
	s_waitcnt lgkmcnt(3)
	v_mfma_f32_16x16x32_bf16 v[28:31], v[200:203], v[184:187], v[28:31]
	v_mfma_f32_16x16x32_bf16 v[24:27], v[204:207], v[184:187], v[24:27]
	s_waitcnt lgkmcnt(2)
	v_mfma_f32_16x16x32_bf16 v[20:23], v[200:203], v[188:191], v[20:23]
	v_mfma_f32_16x16x32_bf16 v[16:19], v[204:207], v[188:191], v[16:19]
	s_waitcnt lgkmcnt(1)
	v_mfma_f32_16x16x32_bf16 v[12:15], v[200:203], v[192:195], v[12:15]
	v_mfma_f32_16x16x32_bf16 v[8:11], v[204:207], v[192:195], v[8:11]
	s_waitcnt lgkmcnt(0)
	v_mfma_f32_16x16x32_bf16 v[4:7], v[200:203], v[196:199], v[4:7]
	v_mfma_f32_16x16x32_bf16 v[0:3], v[204:207], v[196:199], v[0:3]
	s_add_u32 s9, s9, 0xd000
	s_cmp_eq_u32 s9, 0x27000
	s_cselect_b32 s9, 0, s9
	v_add_u32_e32 v164, s9, v97
	v_add_u32_e32 v165, s9, v99
	v_add_u32_e32 v192, v164, v101
	v_add_u32_e32 v196, v165, v101
	v_add_u32_e32 v164, v164, v100
	v_add_u32_e32 v165, v165, v100
	s_waitcnt vmcnt(0) lgkmcnt(0)
	s_barrier
	ds_read_b128 v[152:155], v164 offset:20480
	ds_read_b128 v[156:159], v164 offset:22528
	ds_read_b128 v[108:111], v165
	ds_read_b128 v[112:115], v165 offset:2048
	ds_read_b128 v[116:119], v165 offset:4096
	ds_read_b128 v[120:123], v165 offset:6144
	ds_read_b128 v[124:127], v165 offset:8192
	ds_read_b128 v[132:135], v165 offset:10240
	ds_read_b128 v[136:139], v165 offset:12288
	ds_read_b128 v[140:143], v165 offset:14336
	ds_read_b128 v[144:147], v165 offset:16384
	ds_read_b128 v[148:151], v165 offset:18432
	s_waitcnt lgkmcnt(9)
	v_mfma_f32_16x16x32_bf16 v[76:79], v[152:155], v[108:111], v[76:79]
	v_mfma_f32_16x16x32_bf16 v[72:75], v[156:159], v[108:111], v[72:75]
	ds_read_b128 v[200:203], v192 offset:20480
	s_waitcnt lgkmcnt(9)
	v_mfma_f32_16x16x32_bf16 v[68:71], v[152:155], v[112:115], v[68:71]
	v_mfma_f32_16x16x32_bf16 v[64:67], v[156:159], v[112:115], v[64:67]
	ds_read_b128 v[204:207], v192 offset:22528
	s_waitcnt lgkmcnt(9)
	v_mfma_f32_16x16x32_bf16 v[60:63], v[152:155], v[116:119], v[60:63]
	v_mfma_f32_16x16x32_bf16 v[56:59], v[156:159], v[116:119], v[56:59]
	ds_read_b128 v[160:163], v196
	s_waitcnt lgkmcnt(9)
	v_mfma_f32_16x16x32_bf16 v[52:55], v[152:155], v[120:123], v[52:55]
	v_mfma_f32_16x16x32_bf16 v[48:51], v[156:159], v[120:123], v[48:51]
	ds_read_b128 v[164:167], v196 offset:2048
	s_waitcnt lgkmcnt(9)
	v_mfma_f32_16x16x32_bf16 v[44:47], v[152:155], v[124:127], v[44:47]
	v_mfma_f32_16x16x32_bf16 v[40:43], v[156:159], v[124:127], v[40:43]
	ds_read_b128 v[168:171], v196 offset:4096
	s_waitcnt lgkmcnt(9)
	v_mfma_f32_16x16x32_bf16 v[36:39], v[152:155], v[132:135], v[36:39]
	v_mfma_f32_16x16x32_bf16 v[32:35], v[156:159], v[132:135], v[32:35]
	ds_read_b128 v[172:175], v196 offset:6144
	s_waitcnt lgkmcnt(9)
	v_mfma_f32_16x16x32_bf16 v[28:31], v[152:155], v[136:139], v[28:31]
	v_mfma_f32_16x16x32_bf16 v[24:27], v[156:159], v[136:139], v[24:27]
	ds_read_b128 v[176:179], v196 offset:8192
	s_waitcnt lgkmcnt(9)
	v_mfma_f32_16x16x32_bf16 v[20:23], v[152:155], v[140:143], v[20:23]
	v_mfma_f32_16x16x32_bf16 v[16:19], v[156:159], v[140:143], v[16:19]
	ds_read_b128 v[180:183], v196 offset:10240
	s_waitcnt lgkmcnt(9)
	v_mfma_f32_16x16x32_bf16 v[12:15], v[152:155], v[144:147], v[12:15]
	v_mfma_f32_16x16x32_bf16 v[8:11], v[156:159], v[144:147], v[8:11]
	ds_read_b128 v[184:187], v196 offset:12288
	s_waitcnt lgkmcnt(9)
	v_mfma_f32_16x16x32_bf16 v[4:7], v[152:155], v[148:151], v[4:7]
	v_mfma_f32_16x16x32_bf16 v[0:3], v[156:159], v[148:151], v[0:3]
	ds_read_b128 v[188:191], v196 offset:14336
	ds_read_b128 v[192:195], v196 offset:16384
	ds_read_b128 v[196:199], v196 offset:18432
	s_waitcnt lgkmcnt(9)
	v_mfma_f32_16x16x32_bf16 v[76:79], v[200:203], v[160:163], v[76:79]
	v_mfma_f32_16x16x32_bf16 v[72:75], v[204:207], v[160:163], v[72:75]
	s_waitcnt lgkmcnt(8)
	v_mfma_f32_16x16x32_bf16 v[68:71], v[200:203], v[164:167], v[68:71]
	v_mfma_f32_16x16x32_bf16 v[64:67], v[204:207], v[164:167], v[64:67]
	s_waitcnt lgkmcnt(7)
	v_mfma_f32_16x16x32_bf16 v[60:63], v[200:203], v[168:171], v[60:63]
	v_mfma_f32_16x16x32_bf16 v[56:59], v[204:207], v[168:171], v[56:59]
	s_waitcnt lgkmcnt(6)
	v_mfma_f32_16x16x32_bf16 v[52:55], v[200:203], v[172:175], v[52:55]
	v_mfma_f32_16x16x32_bf16 v[48:51], v[204:207], v[172:175], v[48:51]
	s_waitcnt lgkmcnt(5)
	v_mfma_f32_16x16x32_bf16 v[44:47], v[200:203], v[176:179], v[44:47]
	v_mfma_f32_16x16x32_bf16 v[40:43], v[204:207], v[176:179], v[40:43]
	s_waitcnt lgkmcnt(4)
	v_mfma_f32_16x16x32_bf16 v[36:39], v[200:203], v[180:183], v[36:39]
	v_mfma_f32_16x16x32_bf16 v[32:35], v[204:207], v[180:183], v[32:35]
	s_waitcnt lgkmcnt(3)
	v_mfma_f32_16x16x32_bf16 v[28:31], v[200:203], v[184:187], v[28:31]
	v_mfma_f32_16x16x32_bf16 v[24:27], v[204:207], v[184:187], v[24:27]
	s_waitcnt lgkmcnt(2)
	v_mfma_f32_16x16x32_bf16 v[20:23], v[200:203], v[188:191], v[20:23]
	v_mfma_f32_16x16x32_bf16 v[16:19], v[204:207], v[188:191], v[16:19]
	s_waitcnt lgkmcnt(1)
	v_mfma_f32_16x16x32_bf16 v[12:15], v[200:203], v[192:195], v[12:15]
	v_mfma_f32_16x16x32_bf16 v[8:11], v[204:207], v[192:195], v[8:11]
	s_waitcnt lgkmcnt(0)
	v_mfma_f32_16x16x32_bf16 v[4:7], v[200:203], v[196:199], v[4:7]
	v_mfma_f32_16x16x32_bf16 v[0:3], v[204:207], v[196:199], v[0:3]
	s_add_u32 s9, s9, 0xd000
	s_cmp_eq_u32 s9, 0x27000
	s_cselect_b32 s9, 0, s9
	s_branch .Lg160o_epi

.Lg160d_pskip:
	s_or_b64 exec, exec, s[100:101]
	s_mov_b64 s[12:13], 0x1060080
	v_lshl_add_u64 v[188:189], v[92:93], 0, s[12:13]
	s_add_u32 m0, s98, 0x5000
	s_nop 0
	global_load_lds_dwordx4 v[188:189], off
	s_mov_b64 s[12:13], 0x10b8080
	v_lshl_add_u64 v[188:189], v[92:93], 0, s[12:13]
	s_add_u32 m0, s98, 0x7000
	s_nop 0
	global_load_lds_dwordx4 v[188:189], off
	s_mov_b64 s[12:13], 0x1110080
	v_lshl_add_u64 v[188:189], v[92:93], 0, s[12:13]
	s_add_u32 m0, s98, 0x9000
	s_nop 0
	global_load_lds_dwordx4 v[188:189], off
	s_mov_b64 s[12:13], 0x1168080
	v_lshl_add_u64 v[188:189], v[92:93], 0, s[12:13]
	s_add_u32 m0, s98, 0xb000
	s_nop 0
	global_load_lds_dwordx4 v[188:189], off
	s_cmp_eq_u64 s[4:5], 0
	s_cbranch_scc1 .Lg160d_q
.Lg160d_p:
	v_add_u32_e32 v164, s9, v97
	v_add_u32_e32 v165, s9, v99
	v_add_u32_e32 v192, v164, v101
	v_add_u32_e32 v196, v165, v101
	v_add_u32_e32 v164, v164, v100
	v_add_u32_e32 v165, v165, v100
	s_waitcnt vmcnt(7) lgkmcnt(0)
	s_barrier
	ds_read_b128 v[152:155], v164 offset:20480
	ds_read_b128 v[156:159], v164 offset:22528
	ds_read_b128 v[108:111], v165
	ds_read_b128 v[112:115], v165 offset:2048
	ds_read_b128 v[116:119], v165 offset:4096
	ds_read_b128 v[120:123], v165 offset:6144
	ds_read_b128 v[124:127], v165 offset:8192
	ds_read_b128 v[132:135], v165 offset:10240
	ds_read_b128 v[136:139], v165 offset:12288
	ds_read_b128 v[140:143], v165 offset:14336
	ds_read_b128 v[144:147], v165 offset:16384
	ds_read_b128 v[148:151], v165 offset:18432
	s_waitcnt lgkmcnt(9)
	v_mfma_f32_16x16x32_bf16 v[76:79], v[152:155], v[108:111], v[76:79]
	v_mfma_f32_16x16x32_bf16 v[72:75], v[156:159], v[108:111], v[72:75]
	ds_read_b128 v[200:203], v192 offset:20480
	s_waitcnt lgkmcnt(9)
	v_mfma_f32_16x16x32_bf16 v[68:71], v[152:155], v[112:115], v[68:71]
	v_mfma_f32_16x16x32_bf16 v[64:67], v[156:159], v[112:115], v[64:67]
	ds_read_b128 v[204:207], v192 offset:22528
	s_waitcnt lgkmcnt(9)
	v_mfma_f32_16x16x32_bf16 v[60:63], v[152:155], v[116:119], v[60:63]
	v_mfma_f32_16x16x32_bf16 v[56:59], v[156:159], v[116:119], v[56:59]
	ds_read_b128 v[160:163], v196
	s_waitcnt lgkmcnt(9)
	v_mfma_f32_16x16x32_bf16 v[52:55], v[152:155], v[120:123], v[52:55]
	v_mfma_f32_16x16x32_bf16 v[48:51], v[156:159], v[120:123], v[48:51]
	ds_read_b128 v[164:167], v196 offset:2048
	s_waitcnt lgkmcnt(9)
	v_mfma_f32_16x16x32_bf16 v[44:47], v[152:155], v[124:127], v[44:47]
	v_mfma_f32_16x16x32_bf16 v[40:43], v[156:159], v[124:127], v[40:43]
	ds_read_b128 v[168:171], v196 offset:4096
	s_waitcnt lgkmcnt(9)
	v_mfma_f32_16x16x32_bf16 v[36:39], v[152:155], v[132:135], v[36:39]
	v_mfma_f32_16x16x32_bf16 v[32:35], v[156:159], v[132:135], v[32:35]
	ds_read_b128 v[172:175], v196 offset:6144
	s_waitcnt lgkmcnt(9)
	v_mfma_f32_16x16x32_bf16 v[28:31], v[152:155], v[136:139], v[28:31]
	v_mfma_f32_16x16x32_bf16 v[24:27], v[156:159], v[136:139], v[24:27]
	ds_read_b128 v[176:179], v196 offset:8192
	s_waitcnt lgkmcnt(9)
	v_mfma_f32_16x16x32_bf16 v[20:23], v[152:155], v[140:143], v[20:23]
	v_mfma_f32_16x16x32_bf16 v[16:19], v[156:159], v[140:143], v[16:19]
	ds_read_b128 v[180:183], v196 offset:10240
	s_waitcnt lgkmcnt(9)
	v_mfma_f32_16x16x32_bf16 v[12:15], v[152:155], v[144:147], v[12:15]
	v_mfma_f32_16x16x32_bf16 v[8:11], v[156:159], v[144:147], v[8:11]
	ds_read_b128 v[184:187], v196 offset:12288
	s_waitcnt lgkmcnt(9)
	v_mfma_f32_16x16x32_bf16 v[4:7], v[152:155], v[148:151], v[4:7]
	v_mfma_f32_16x16x32_bf16 v[0:3], v[156:159], v[148:151], v[0:3]
	ds_read_b128 v[188:191], v196 offset:14336
	ds_read_b128 v[192:195], v196 offset:16384
	ds_read_b128 v[196:199], v196 offset:18432
	s_waitcnt lgkmcnt(9)
	v_mfma_f32_16x16x32_bf16 v[76:79], v[200:203], v[160:163], v[76:79]
	v_mfma_f32_16x16x32_bf16 v[72:75], v[204:207], v[160:163], v[72:75]
	s_waitcnt lgkmcnt(8)
	v_mfma_f32_16x16x32_bf16 v[68:71], v[200:203], v[164:167], v[68:71]
	v_mfma_f32_16x16x32_bf16 v[64:67], v[204:207], v[164:167], v[64:67]
	s_waitcnt lgkmcnt(7)
	v_mfma_f32_16x16x32_bf16 v[60:63], v[200:203], v[168:171], v[60:63]
	v_mfma_f32_16x16x32_bf16 v[56:59], v[204:207], v[168:171], v[56:59]
	s_waitcnt lgkmcnt(6)
	v_mfma_f32_16x16x32_bf16 v[52:55], v[200:203], v[172:175], v[52:55]
	v_mfma_f32_16x16x32_bf16 v[48:51], v[204:207], v[172:175], v[48:51]
	s_waitcnt lgkmcnt(5)
	v_mfma_f32_16x16x32_bf16 v[44:47], v[200:203], v[176:179], v[44:47]
	v_mfma_f32_16x16x32_bf16 v[40:43], v[204:207], v[176:179], v[40:43]
	s_waitcnt lgkmcnt(4)
	v_mfma_f32_16x16x32_bf16 v[36:39], v[200:203], v[180:183], v[36:39]
	v_mfma_f32_16x16x32_bf16 v[32:35], v[204:207], v[180:183], v[32:35]
	s_waitcnt lgkmcnt(3)
	v_mfma_f32_16x16x32_bf16 v[28:31], v[200:203], v[184:187], v[28:31]
	v_mfma_f32_16x16x32_bf16 v[24:27], v[204:207], v[184:187], v[24:27]
	s_waitcnt lgkmcnt(2)
	v_mfma_f32_16x16x32_bf16 v[20:23], v[200:203], v[188:191], v[20:23]
	v_mfma_f32_16x16x32_bf16 v[16:19], v[204:207], v[188:191], v[16:19]
	s_waitcnt lgkmcnt(1)
	v_mfma_f32_16x16x32_bf16 v[12:15], v[200:203], v[192:195], v[12:15]
	v_mfma_f32_16x16x32_bf16 v[8:11], v[204:207], v[192:195], v[8:11]
	s_waitcnt lgkmcnt(0)
	v_mfma_f32_16x16x32_bf16 v[4:7], v[200:203], v[196:199], v[4:7]
	v_mfma_f32_16x16x32_bf16 v[0:3], v[204:207], v[196:199], v[0:3]
	s_add_u32 s12, s9, 0x1a000
	s_cmp_ge_u32 s12, 0x27000
	s_cselect_b32 s13, 0x27000, 0
	s_sub_u32 s12, s12, s13
	v_add_u32_e32 v168, s12, v98
	s_add_u32 s12, s10, 0x80
	s_addc_u32 s13, s11, 0
	v_lshl_add_u64 v[94:95], v[90:91], 0, s[12:13]
	v_lshl_add_u64 v[186:187], v[92:93], 0, s[12:13]
	v_readfirstlane_b32 s98, v168
	s_mov_b64 s[12:13], 0x7c31080
	v_lshl_add_u64 v[188:189], v[94:95], 0, s[12:13]
	s_mov_b32 m0, s98
	s_nop 0
	global_load_lds_dwordx4 v[188:189], off
	s_mov_b64 s[12:13], 0x7c89080
	v_lshl_add_u64 v[188:189], v[94:95], 0, s[12:13]
	s_add_u32 m0, s98, 0x2000
	s_nop 0
	global_load_lds_dwordx4 v[188:189], off
	s_mov_b64 s[12:13], 0x7ce1080
	v_lshl_add_u64 v[188:189], v[94:95], 0, s[12:13]
	s_add_u32 m0, s98, 0x4000
	s_nop 0
	global_load_lds_dwordx4 v[188:189], off
	s_mov_b64 s[12:13], 0x1060080
	v_lshl_add_u64 v[188:189], v[186:187], 0, s[12:13]
	s_add_u32 m0, s98, 0x5000
	s_nop 0
	global_load_lds_dwordx4 v[188:189], off
	s_mov_b64 s[12:13], 0x10b8080
	v_lshl_add_u64 v[188:189], v[186:187], 0, s[12:13]
	s_add_u32 m0, s98, 0x7000
	s_nop 0
	global_load_lds_dwordx4 v[188:189], off
	s_mov_b64 s[12:13], 0x1110080
	v_lshl_add_u64 v[188:189], v[186:187], 0, s[12:13]
	s_add_u32 m0, s98, 0x9000
	s_nop 0
	global_load_lds_dwordx4 v[188:189], off
	s_mov_b64 s[12:13], 0x1168080
	v_lshl_add_u64 v[188:189], v[186:187], 0, s[12:13]
	s_add_u32 m0, s98, 0xb000
	s_nop 0
	global_load_lds_dwordx4 v[188:189], off
	s_add_u32 s9, s9, 0xd000
	s_cmp_eq_u32 s9, 0x27000
	s_cselect_b32 s9, 0, s9
	s_add_u32 s10, s10, 0x80
	s_addc_u32 s11, s11, 0
	s_cmpk_eq_i32 s10, 0x1500
	s_cbranch_scc0 .Lg160d_p
	v_add_u32_e32 v164, s9, v97
	v_add_u32_e32 v165, s9, v99
	v_add_u32_e32 v192, v164, v101
	v_add_u32_e32 v196, v165, v101
	v_add_u32_e32 v164, v164, v100
	v_add_u32_e32 v165, v165, v100
	s_waitcnt vmcnt(7) lgkmcnt(0)
	s_barrier
	ds_read_b128 v[152:155], v164 offset:20480
	ds_read_b128 v[156:159], v164 offset:22528
	ds_read_b128 v[108:111], v165
	ds_read_b128 v[112:115], v165 offset:2048
	ds_read_b128 v[116:119], v165 offset:4096
	ds_read_b128 v[120:123], v165 offset:6144
	ds_read_b128 v[124:127], v165 offset:8192
	ds_read_b128 v[132:135], v165 offset:10240
	ds_read_b128 v[136:139], v165 offset:12288
	ds_read_b128 v[140:143], v165 offset:14336
	ds_read_b128 v[144:147], v165 offset:16384
	ds_read_b128 v[148:151], v165 offset:18432
	s_waitcnt lgkmcnt(9)
	v_mfma_f32_16x16x32_bf16 v[76:79], v[152:155], v[108:111], v[76:79]
	v_mfma_f32_16x16x32_bf16 v[72:75], v[156:159], v[108:111], v[72:75]
	ds_read_b128 v[200:203], v192 offset:20480
	s_waitcnt lgkmcnt(9)
	v_mfma_f32_16x16x32_bf16 v[68:71], v[152:155], v[112:115], v[68:71]
	v_mfma_f32_16x16x32_bf16 v[64:67], v[156:159], v[112:115], v[64:67]
	ds_read_b128 v[204:207], v192 offset:22528
	s_waitcnt lgkmcnt(9)
	v_mfma_f32_16x16x32_bf16 v[60:63], v[152:155], v[116:119], v[60:63]
	v_mfma_f32_16x16x32_bf16 v[56:59], v[156:159], v[116:119], v[56:59]
	ds_read_b128 v[160:163], v196
	s_waitcnt lgkmcnt(9)
	v_mfma_f32_16x16x32_bf16 v[52:55], v[152:155], v[120:123], v[52:55]
	v_mfma_f32_16x16x32_bf16 v[48:51], v[156:159], v[120:123], v[48:51]
	ds_read_b128 v[164:167], v196 offset:2048
	s_waitcnt lgkmcnt(9)
	v_mfma_f32_16x16x32_bf16 v[44:47], v[152:155], v[124:127], v[44:47]
	v_mfma_f32_16x16x32_bf16 v[40:43], v[156:159], v[124:127], v[40:43]
	ds_read_b128 v[168:171], v196 offset:4096
	s_waitcnt lgkmcnt(9)
	v_mfma_f32_16x16x32_bf16 v[36:39], v[152:155], v[132:135], v[36:39]
	v_mfma_f32_16x16x32_bf16 v[32:35], v[156:159], v[132:135], v[32:35]
	ds_read_b128 v[172:175], v196 offset:6144
	s_waitcnt lgkmcnt(9)
	v_mfma_f32_16x16x32_bf16 v[28:31], v[152:155], v[136:139], v[28:31]
	v_mfma_f32_16x16x32_bf16 v[24:27], v[156:159], v[136:139], v[24:27]
	ds_read_b128 v[176:179], v196 offset:8192
	s_waitcnt lgkmcnt(9)
	v_mfma_f32_16x16x32_bf16 v[20:23], v[152:155], v[140:143], v[20:23]
	v_mfma_f32_16x16x32_bf16 v[16:19], v[156:159], v[140:143], v[16:19]
	ds_read_b128 v[180:183], v196 offset:10240
	s_waitcnt lgkmcnt(9)
	v_mfma_f32_16x16x32_bf16 v[12:15], v[152:155], v[144:147], v[12:15]
	v_mfma_f32_16x16x32_bf16 v[8:11], v[156:159], v[144:147], v[8:11]
	ds_read_b128 v[184:187], v196 offset:12288
	s_waitcnt lgkmcnt(9)
	v_mfma_f32_16x16x32_bf16 v[4:7], v[152:155], v[148:151], v[4:7]
	v_mfma_f32_16x16x32_bf16 v[0:3], v[156:159], v[148:151], v[0:3]
	ds_read_b128 v[188:191], v196 offset:14336
	ds_read_b128 v[192:195], v196 offset:16384
	ds_read_b128 v[196:199], v196 offset:18432
	s_waitcnt lgkmcnt(9)
	v_mfma_f32_16x16x32_bf16 v[76:79], v[200:203], v[160:163], v[76:79]
	v_mfma_f32_16x16x32_bf16 v[72:75], v[204:207], v[160:163], v[72:75]
	s_waitcnt lgkmcnt(8)
	v_mfma_f32_16x16x32_bf16 v[68:71], v[200:203], v[164:167], v[68:71]
	v_mfma_f32_16x16x32_bf16 v[64:67], v[204:207], v[164:167], v[64:67]
	s_waitcnt lgkmcnt(7)
	v_mfma_f32_16x16x32_bf16 v[60:63], v[200:203], v[168:171], v[60:63]
	v_mfma_f32_16x16x32_bf16 v[56:59], v[204:207], v[168:171], v[56:59]
	s_waitcnt lgkmcnt(6)
	v_mfma_f32_16x16x32_bf16 v[52:55], v[200:203], v[172:175], v[52:55]
	v_mfma_f32_16x16x32_bf16 v[48:51], v[204:207], v[172:175], v[48:51]
	s_waitcnt lgkmcnt(5)
	v_mfma_f32_16x16x32_bf16 v[44:47], v[200:203], v[176:179], v[44:47]
	v_mfma_f32_16x16x32_bf16 v[40:43], v[204:207], v[176:179], v[40:43]
	s_waitcnt lgkmcnt(4)
	v_mfma_f32_16x16x32_bf16 v[36:39], v[200:203], v[180:183], v[36:39]
	v_mfma_f32_16x16x32_bf16 v[32:35], v[204:207], v[180:183], v[32:35]
	s_waitcnt lgkmcnt(3)
	v_mfma_f32_16x16x32_bf16 v[28:31], v[200:203], v[184:187], v[28:31]
	v_mfma_f32_16x16x32_bf16 v[24:27], v[204:207], v[184:187], v[24:27]
	s_waitcnt lgkmcnt(2)
	v_mfma_f32_16x16x32_bf16 v[20:23], v[200:203], v[188:191], v[20:23]
	v_mfma_f32_16x16x32_bf16 v[16:19], v[204:207], v[188:191], v[16:19]
	s_waitcnt lgkmcnt(1)
	v_mfma_f32_16x16x32_bf16 v[12:15], v[200:203], v[192:195], v[12:15]
	v_mfma_f32_16x16x32_bf16 v[8:11], v[204:207], v[192:195], v[8:11]
	s_waitcnt lgkmcnt(0)
	v_mfma_f32_16x16x32_bf16 v[4:7], v[200:203], v[196:199], v[4:7]
	v_mfma_f32_16x16x32_bf16 v[0:3], v[204:207], v[196:199], v[0:3]
	s_add_u32 s9, s9, 0xd000
	s_cmp_eq_u32 s9, 0x27000
	s_cselect_b32 s9, 0, s9
	v_add_u32_e32 v164, s9, v97
	v_add_u32_e32 v165, s9, v99
	v_add_u32_e32 v192, v164, v101
	v_add_u32_e32 v196, v165, v101
	v_add_u32_e32 v164, v164, v100
	v_add_u32_e32 v165, v165, v100
	s_waitcnt vmcnt(0) lgkmcnt(0)
	s_barrier
	ds_read_b128 v[152:155], v164 offset:20480
	ds_read_b128 v[156:159], v164 offset:22528
	ds_read_b128 v[108:111], v165
	ds_read_b128 v[112:115], v165 offset:2048
	ds_read_b128 v[116:119], v165 offset:4096
	ds_read_b128 v[120:123], v165 offset:6144
	ds_read_b128 v[124:127], v165 offset:8192
	ds_read_b128 v[132:135], v165 offset:10240
	ds_read_b128 v[136:139], v165 offset:12288
	ds_read_b128 v[140:143], v165 offset:14336
	ds_read_b128 v[144:147], v165 offset:16384
	ds_read_b128 v[148:151], v165 offset:18432
	s_waitcnt lgkmcnt(9)
	v_mfma_f32_16x16x32_bf16 v[76:79], v[152:155], v[108:111], v[76:79]
	v_mfma_f32_16x16x32_bf16 v[72:75], v[156:159], v[108:111], v[72:75]
	ds_read_b128 v[200:203], v192 offset:20480
	s_waitcnt lgkmcnt(9)
	v_mfma_f32_16x16x32_bf16 v[68:71], v[152:155], v[112:115], v[68:71]
	v_mfma_f32_16x16x32_bf16 v[64:67], v[156:159], v[112:115], v[64:67]
	ds_read_b128 v[204:207], v192 offset:22528
	s_waitcnt lgkmcnt(9)
	v_mfma_f32_16x16x32_bf16 v[60:63], v[152:155], v[116:119], v[60:63]
	v_mfma_f32_16x16x32_bf16 v[56:59], v[156:159], v[116:119], v[56:59]
	ds_read_b128 v[160:163], v196
	s_waitcnt lgkmcnt(9)
	v_mfma_f32_16x16x32_bf16 v[52:55], v[152:155], v[120:123], v[52:55]
	v_mfma_f32_16x16x32_bf16 v[48:51], v[156:159], v[120:123], v[48:51]
	ds_read_b128 v[164:167], v196 offset:2048
	s_waitcnt lgkmcnt(9)
	v_mfma_f32_16x16x32_bf16 v[44:47], v[152:155], v[124:127], v[44:47]
	v_mfma_f32_16x16x32_bf16 v[40:43], v[156:159], v[124:127], v[40:43]
	ds_read_b128 v[168:171], v196 offset:4096
	s_waitcnt lgkmcnt(9)
	v_mfma_f32_16x16x32_bf16 v[36:39], v[152:155], v[132:135], v[36:39]
	v_mfma_f32_16x16x32_bf16 v[32:35], v[156:159], v[132:135], v[32:35]
	ds_read_b128 v[172:175], v196 offset:6144
	s_waitcnt lgkmcnt(9)
	v_mfma_f32_16x16x32_bf16 v[28:31], v[152:155], v[136:139], v[28:31]
	v_mfma_f32_16x16x32_bf16 v[24:27], v[156:159], v[136:139], v[24:27]
	ds_read_b128 v[176:179], v196 offset:8192
	s_waitcnt lgkmcnt(9)
	v_mfma_f32_16x16x32_bf16 v[20:23], v[152:155], v[140:143], v[20:23]
	v_mfma_f32_16x16x32_bf16 v[16:19], v[156:159], v[140:143], v[16:19]
	ds_read_b128 v[180:183], v196 offset:10240
	s_waitcnt lgkmcnt(9)
	v_mfma_f32_16x16x32_bf16 v[12:15], v[152:155], v[144:147], v[12:15]
	v_mfma_f32_16x16x32_bf16 v[8:11], v[156:159], v[144:147], v[8:11]
	ds_read_b128 v[184:187], v196 offset:12288
	s_waitcnt lgkmcnt(9)
	v_mfma_f32_16x16x32_bf16 v[4:7], v[152:155], v[148:151], v[4:7]
	v_mfma_f32_16x16x32_bf16 v[0:3], v[156:159], v[148:151], v[0:3]
	ds_read_b128 v[188:191], v196 offset:14336
	ds_read_b128 v[192:195], v196 offset:16384
	ds_read_b128 v[196:199], v196 offset:18432
	s_waitcnt lgkmcnt(9)
	v_mfma_f32_16x16x32_bf16 v[76:79], v[200:203], v[160:163], v[76:79]
	v_mfma_f32_16x16x32_bf16 v[72:75], v[204:207], v[160:163], v[72:75]
	s_waitcnt lgkmcnt(8)
	v_mfma_f32_16x16x32_bf16 v[68:71], v[200:203], v[164:167], v[68:71]
	v_mfma_f32_16x16x32_bf16 v[64:67], v[204:207], v[164:167], v[64:67]
	s_waitcnt lgkmcnt(7)
	v_mfma_f32_16x16x32_bf16 v[60:63], v[200:203], v[168:171], v[60:63]
	v_mfma_f32_16x16x32_bf16 v[56:59], v[204:207], v[168:171], v[56:59]
	s_waitcnt lgkmcnt(6)
	v_mfma_f32_16x16x32_bf16 v[52:55], v[200:203], v[172:175], v[52:55]
	v_mfma_f32_16x16x32_bf16 v[48:51], v[204:207], v[172:175], v[48:51]
	s_waitcnt lgkmcnt(5)
	v_mfma_f32_16x16x32_bf16 v[44:47], v[200:203], v[176:179], v[44:47]
	v_mfma_f32_16x16x32_bf16 v[40:43], v[204:207], v[176:179], v[40:43]
	s_waitcnt lgkmcnt(4)
	v_mfma_f32_16x16x32_bf16 v[36:39], v[200:203], v[180:183], v[36:39]
	v_mfma_f32_16x16x32_bf16 v[32:35], v[204:207], v[180:183], v[32:35]
	s_waitcnt lgkmcnt(3)
	v_mfma_f32_16x16x32_bf16 v[28:31], v[200:203], v[184:187], v[28:31]
	v_mfma_f32_16x16x32_bf16 v[24:27], v[204:207], v[184:187], v[24:27]
	s_waitcnt lgkmcnt(2)
	v_mfma_f32_16x16x32_bf16 v[20:23], v[200:203], v[188:191], v[20:23]
	v_mfma_f32_16x16x32_bf16 v[16:19], v[204:207], v[188:191], v[16:19]
	s_waitcnt lgkmcnt(1)
	v_mfma_f32_16x16x32_bf16 v[12:15], v[200:203], v[192:195], v[12:15]
	v_mfma_f32_16x16x32_bf16 v[8:11], v[204:207], v[192:195], v[8:11]
	s_waitcnt lgkmcnt(0)
	v_mfma_f32_16x16x32_bf16 v[4:7], v[200:203], v[196:199], v[4:7]
	v_mfma_f32_16x16x32_bf16 v[0:3], v[204:207], v[196:199], v[0:3]
	s_add_u32 s9, s9, 0xd000
	s_cmp_eq_u32 s9, 0x27000
	s_cselect_b32 s9, 0, s9
	s_branch .Lg160d_epi
.Lg160d_q:
	s_add_u32 s12, s9, 0x1a000
	s_cmp_ge_u32 s12, 0x27000
	s_cselect_b32 s13, 0x27000, 0
	s_sub_u32 s12, s12, s13
	v_add_u32_e32 v168, s12, v98
	s_add_u32 s12, s10, 0x80
	s_addc_u32 s13, s11, 0
	v_lshl_add_u64 v[94:95], v[90:91], 0, s[12:13]
	v_lshl_add_u64 v[186:187], v[92:93], 0, s[12:13]
	v_readfirstlane_b32 s98, v168
	v_add_u32_e32 v164, s9, v97
	v_add_u32_e32 v165, s9, v99
	v_add_u32_e32 v192, v164, v101
	v_add_u32_e32 v196, v165, v101
	v_add_u32_e32 v164, v164, v100
	v_add_u32_e32 v165, v165, v100
	s_waitcnt vmcnt(6) lgkmcnt(0)
	s_barrier
	s_mov_b64 s[12:13], 0x7c31080
	v_lshl_add_u64 v[188:189], v[94:95], 0, s[12:13]
	s_mov_b32 m0, s98
	s_nop 0
	global_load_lds_dwordx4 v[188:189], off
	s_mov_b64 s[12:13], 0x7c89080
	v_lshl_add_u64 v[188:189], v[94:95], 0, s[12:13]
	s_add_u32 m0, s98, 0x2000
	s_nop 0
	global_load_lds_dwordx4 v[188:189], off
	s_mov_b64 s[12:13], 0x1060080
	v_lshl_add_u64 v[188:189], v[186:187], 0, s[12:13]
	s_add_u32 m0, s98, 0x5000
	s_nop 0
	global_load_lds_dwordx4 v[188:189], off
	s_mov_b64 s[12:13], 0x10b8080
	v_lshl_add_u64 v[188:189], v[186:187], 0, s[12:13]
	s_add_u32 m0, s98, 0x7000
	s_nop 0
	global_load_lds_dwordx4 v[188:189], off
	s_mov_b64 s[12:13], 0x1110080
	v_lshl_add_u64 v[188:189], v[186:187], 0, s[12:13]
	s_add_u32 m0, s98, 0x9000
	s_nop 0
	global_load_lds_dwordx4 v[188:189], off
	s_mov_b64 s[12:13], 0x1168080
	v_lshl_add_u64 v[188:189], v[186:187], 0, s[12:13]
	s_add_u32 m0, s98, 0xb000
	s_nop 0
	global_load_lds_dwordx4 v[188:189], off
	ds_read_b128 v[152:155], v164 offset:20480
	ds_read_b128 v[156:159], v164 offset:22528
	ds_read_b128 v[108:111], v165
	ds_read_b128 v[112:115], v165 offset:2048
	ds_read_b128 v[116:119], v165 offset:4096
	ds_read_b128 v[120:123], v165 offset:6144
	ds_read_b128 v[124:127], v165 offset:8192
	ds_read_b128 v[132:135], v165 offset:10240
	ds_read_b128 v[136:139], v165 offset:12288
	ds_read_b128 v[140:143], v165 offset:14336
	ds_read_b128 v[144:147], v165 offset:16384
	ds_read_b128 v[148:151], v165 offset:18432
	s_waitcnt lgkmcnt(9)
	v_mfma_f32_16x16x32_bf16 v[76:79], v[152:155], v[108:111], v[76:79]
	v_mfma_f32_16x16x32_bf16 v[72:75], v[156:159], v[108:111], v[72:75]
	ds_read_b128 v[200:203], v192 offset:20480
	s_waitcnt lgkmcnt(9)
	v_mfma_f32_16x16x32_bf16 v[68:71], v[152:155], v[112:115], v[68:71]
	v_mfma_f32_16x16x32_bf16 v[64:67], v[156:159], v[112:115], v[64:67]
	ds_read_b128 v[204:207], v192 offset:22528
	s_waitcnt lgkmcnt(9)
	v_mfma_f32_16x16x32_bf16 v[60:63], v[152:155], v[116:119], v[60:63]
	v_mfma_f32_16x16x32_bf16 v[56:59], v[156:159], v[116:119], v[56:59]
	ds_read_b128 v[160:163], v196
	s_waitcnt lgkmcnt(9)
	v_mfma_f32_16x16x32_bf16 v[52:55], v[152:155], v[120:123], v[52:55]
	v_mfma_f32_16x16x32_bf16 v[48:51], v[156:159], v[120:123], v[48:51]
	ds_read_b128 v[164:167], v196 offset:2048
	s_waitcnt lgkmcnt(9)
	v_mfma_f32_16x16x32_bf16 v[44:47], v[152:155], v[124:127], v[44:47]
	v_mfma_f32_16x16x32_bf16 v[40:43], v[156:159], v[124:127], v[40:43]
	ds_read_b128 v[168:171], v196 offset:4096
	s_waitcnt lgkmcnt(9)
	v_mfma_f32_16x16x32_bf16 v[36:39], v[152:155], v[132:135], v[36:39]
	v_mfma_f32_16x16x32_bf16 v[32:35], v[156:159], v[132:135], v[32:35]
	ds_read_b128 v[172:175], v196 offset:6144
	s_waitcnt lgkmcnt(9)
	v_mfma_f32_16x16x32_bf16 v[28:31], v[152:155], v[136:139], v[28:31]
	v_mfma_f32_16x16x32_bf16 v[24:27], v[156:159], v[136:139], v[24:27]
	ds_read_b128 v[176:179], v196 offset:8192
	s_waitcnt lgkmcnt(9)
	v_mfma_f32_16x16x32_bf16 v[20:23], v[152:155], v[140:143], v[20:23]
	v_mfma_f32_16x16x32_bf16 v[16:19], v[156:159], v[140:143], v[16:19]
	ds_read_b128 v[180:183], v196 offset:10240
	s_waitcnt lgkmcnt(9)
	v_mfma_f32_16x16x32_bf16 v[12:15], v[152:155], v[144:147], v[12:15]
	v_mfma_f32_16x16x32_bf16 v[8:11], v[156:159], v[144:147], v[8:11]
	ds_read_b128 v[184:187], v196 offset:12288
	s_waitcnt lgkmcnt(9)
	v_mfma_f32_16x16x32_bf16 v[4:7], v[152:155], v[148:151], v[4:7]
	v_mfma_f32_16x16x32_bf16 v[0:3], v[156:159], v[148:151], v[0:3]
	ds_read_b128 v[188:191], v196 offset:14336
	ds_read_b128 v[192:195], v196 offset:16384
	ds_read_b128 v[196:199], v196 offset:18432
	s_waitcnt lgkmcnt(9)
	v_mfma_f32_16x16x32_bf16 v[76:79], v[200:203], v[160:163], v[76:79]
	v_mfma_f32_16x16x32_bf16 v[72:75], v[204:207], v[160:163], v[72:75]
	s_waitcnt lgkmcnt(8)
	v_mfma_f32_16x16x32_bf16 v[68:71], v[200:203], v[164:167], v[68:71]
	v_mfma_f32_16x16x32_bf16 v[64:67], v[204:207], v[164:167], v[64:67]
	s_waitcnt lgkmcnt(7)
	v_mfma_f32_16x16x32_bf16 v[60:63], v[200:203], v[168:171], v[60:63]
	v_mfma_f32_16x16x32_bf16 v[56:59], v[204:207], v[168:171], v[56:59]
	s_waitcnt lgkmcnt(6)
	v_mfma_f32_16x16x32_bf16 v[52:55], v[200:203], v[172:175], v[52:55]
	v_mfma_f32_16x16x32_bf16 v[48:51], v[204:207], v[172:175], v[48:51]
	s_waitcnt lgkmcnt(5)
	v_mfma_f32_16x16x32_bf16 v[44:47], v[200:203], v[176:179], v[44:47]
	v_mfma_f32_16x16x32_bf16 v[40:43], v[204:207], v[176:179], v[40:43]
	s_waitcnt lgkmcnt(4)
	v_mfma_f32_16x16x32_bf16 v[36:39], v[200:203], v[180:183], v[36:39]
	v_mfma_f32_16x16x32_bf16 v[32:35], v[204:207], v[180:183], v[32:35]
	s_waitcnt lgkmcnt(3)
	v_mfma_f32_16x16x32_bf16 v[28:31], v[200:203], v[184:187], v[28:31]
	v_mfma_f32_16x16x32_bf16 v[24:27], v[204:207], v[184:187], v[24:27]
	s_waitcnt lgkmcnt(2)
	v_mfma_f32_16x16x32_bf16 v[20:23], v[200:203], v[188:191], v[20:23]
	v_mfma_f32_16x16x32_bf16 v[16:19], v[204:207], v[188:191], v[16:19]
	s_waitcnt lgkmcnt(1)
	v_mfma_f32_16x16x32_bf16 v[12:15], v[200:203], v[192:195], v[12:15]
	v_mfma_f32_16x16x32_bf16 v[8:11], v[204:207], v[192:195], v[8:11]
	s_waitcnt lgkmcnt(0)
	v_mfma_f32_16x16x32_bf16 v[4:7], v[200:203], v[196:199], v[4:7]
	v_mfma_f32_16x16x32_bf16 v[0:3], v[204:207], v[196:199], v[0:3]
	s_add_u32 s9, s9, 0xd000
	s_cmp_eq_u32 s9, 0x27000
	s_cselect_b32 s9, 0, s9
	s_add_u32 s10, s10, 0x80
	s_addc_u32 s11, s11, 0
	s_cmpk_eq_i32 s10, 0x1500
	s_cbranch_scc0 .Lg160d_q
	v_add_u32_e32 v164, s9, v97
	v_add_u32_e32 v165, s9, v99
	v_add_u32_e32 v192, v164, v101
	v_add_u32_e32 v196, v165, v101
	v_add_u32_e32 v164, v164, v100
	v_add_u32_e32 v165, v165, v100
	s_waitcnt vmcnt(6) lgkmcnt(0)
	s_barrier
	ds_read_b128 v[152:155], v164 offset:20480
	ds_read_b128 v[156:159], v164 offset:22528
	ds_read_b128 v[108:111], v165
	ds_read_b128 v[112:115], v165 offset:2048
	ds_read_b128 v[116:119], v165 offset:4096
	ds_read_b128 v[120:123], v165 offset:6144
	ds_read_b128 v[124:127], v165 offset:8192
	ds_read_b128 v[132:135], v165 offset:10240
	ds_read_b128 v[136:139], v165 offset:12288
	ds_read_b128 v[140:143], v165 offset:14336
	ds_read_b128 v[144:147], v165 offset:16384
	ds_read_b128 v[148:151], v165 offset:18432
	s_waitcnt lgkmcnt(9)
	v_mfma_f32_16x16x32_bf16 v[76:79], v[152:155], v[108:111], v[76:79]
	v_mfma_f32_16x16x32_bf16 v[72:75], v[156:159], v[108:111], v[72:75]
	ds_read_b128 v[200:203], v192 offset:20480
	s_waitcnt lgkmcnt(9)
	v_mfma_f32_16x16x32_bf16 v[68:71], v[152:155], v[112:115], v[68:71]
	v_mfma_f32_16x16x32_bf16 v[64:67], v[156:159], v[112:115], v[64:67]
	ds_read_b128 v[204:207], v192 offset:22528
	s_waitcnt lgkmcnt(9)
	v_mfma_f32_16x16x32_bf16 v[60:63], v[152:155], v[116:119], v[60:63]
	v_mfma_f32_16x16x32_bf16 v[56:59], v[156:159], v[116:119], v[56:59]
	ds_read_b128 v[160:163], v196
	s_waitcnt lgkmcnt(9)
	v_mfma_f32_16x16x32_bf16 v[52:55], v[152:155], v[120:123], v[52:55]
	v_mfma_f32_16x16x32_bf16 v[48:51], v[156:159], v[120:123], v[48:51]
	ds_read_b128 v[164:167], v196 offset:2048
	s_waitcnt lgkmcnt(9)
	v_mfma_f32_16x16x32_bf16 v[44:47], v[152:155], v[124:127], v[44:47]
	v_mfma_f32_16x16x32_bf16 v[40:43], v[156:159], v[124:127], v[40:43]
	ds_read_b128 v[168:171], v196 offset:4096
	s_waitcnt lgkmcnt(9)
	v_mfma_f32_16x16x32_bf16 v[36:39], v[152:155], v[132:135], v[36:39]
	v_mfma_f32_16x16x32_bf16 v[32:35], v[156:159], v[132:135], v[32:35]
	ds_read_b128 v[172:175], v196 offset:6144
	s_waitcnt lgkmcnt(9)
	v_mfma_f32_16x16x32_bf16 v[28:31], v[152:155], v[136:139], v[28:31]
	v_mfma_f32_16x16x32_bf16 v[24:27], v[156:159], v[136:139], v[24:27]
	ds_read_b128 v[176:179], v196 offset:8192
	s_waitcnt lgkmcnt(9)
	v_mfma_f32_16x16x32_bf16 v[20:23], v[152:155], v[140:143], v[20:23]
	v_mfma_f32_16x16x32_bf16 v[16:19], v[156:159], v[140:143], v[16:19]
	ds_read_b128 v[180:183], v196 offset:10240
	s_waitcnt lgkmcnt(9)
	v_mfma_f32_16x16x32_bf16 v[12:15], v[152:155], v[144:147], v[12:15]
	v_mfma_f32_16x16x32_bf16 v[8:11], v[156:159], v[144:147], v[8:11]
	ds_read_b128 v[184:187], v196 offset:12288
	s_waitcnt lgkmcnt(9)
	v_mfma_f32_16x16x32_bf16 v[4:7], v[152:155], v[148:151], v[4:7]
	v_mfma_f32_16x16x32_bf16 v[0:3], v[156:159], v[148:151], v[0:3]
	ds_read_b128 v[188:191], v196 offset:14336
	ds_read_b128 v[192:195], v196 offset:16384
	ds_read_b128 v[196:199], v196 offset:18432
	s_waitcnt lgkmcnt(9)
	v_mfma_f32_16x16x32_bf16 v[76:79], v[200:203], v[160:163], v[76:79]
	v_mfma_f32_16x16x32_bf16 v[72:75], v[204:207], v[160:163], v[72:75]
	s_waitcnt lgkmcnt(8)
	v_mfma_f32_16x16x32_bf16 v[68:71], v[200:203], v[164:167], v[68:71]
	v_mfma_f32_16x16x32_bf16 v[64:67], v[204:207], v[164:167], v[64:67]
	s_waitcnt lgkmcnt(7)
	v_mfma_f32_16x16x32_bf16 v[60:63], v[200:203], v[168:171], v[60:63]
	v_mfma_f32_16x16x32_bf16 v[56:59], v[204:207], v[168:171], v[56:59]
	s_waitcnt lgkmcnt(6)
	v_mfma_f32_16x16x32_bf16 v[52:55], v[200:203], v[172:175], v[52:55]
	v_mfma_f32_16x16x32_bf16 v[48:51], v[204:207], v[172:175], v[48:51]
	s_waitcnt lgkmcnt(5)
	v_mfma_f32_16x16x32_bf16 v[44:47], v[200:203], v[176:179], v[44:47]
	v_mfma_f32_16x16x32_bf16 v[40:43], v[204:207], v[176:179], v[40:43]
	s_waitcnt lgkmcnt(4)
	v_mfma_f32_16x16x32_bf16 v[36:39], v[200:203], v[180:183], v[36:39]
	v_mfma_f32_16x16x32_bf16 v[32:35], v[204:207], v[180:183], v[32:35]
	s_waitcnt lgkmcnt(3)
	v_mfma_f32_16x16x32_bf16 v[28:31], v[200:203], v[184:187], v[28:31]
	v_mfma_f32_16x16x32_bf16 v[24:27], v[204:207], v[184:187], v[24:27]
	s_waitcnt lgkmcnt(2)
	v_mfma_f32_16x16x32_bf16 v[20:23], v[200:203], v[188:191], v[20:23]
	v_mfma_f32_16x16x32_bf16 v[16:19], v[204:207], v[188:191], v[16:19]
	s_waitcnt lgkmcnt(1)
	v_mfma_f32_16x16x32_bf16 v[12:15], v[200:203], v[192:195], v[12:15]
	v_mfma_f32_16x16x32_bf16 v[8:11], v[204:207], v[192:195], v[8:11]
	s_waitcnt lgkmcnt(0)
	v_mfma_f32_16x16x32_bf16 v[4:7], v[200:203], v[196:199], v[4:7]
	v_mfma_f32_16x16x32_bf16 v[0:3], v[204:207], v[196:199], v[0:3]
	s_add_u32 s9, s9, 0xd000
	s_cmp_eq_u32 s9, 0x27000
	s_cselect_b32 s9, 0, s9
	v_add_u32_e32 v164, s9, v97
	v_add_u32_e32 v165, s9, v99
	v_add_u32_e32 v192, v164, v101
	v_add_u32_e32 v196, v165, v101
	v_add_u32_e32 v164, v164, v100
	v_add_u32_e32 v165, v165, v100
	s_waitcnt vmcnt(0) lgkmcnt(0)
	s_barrier
	ds_read_b128 v[152:155], v164 offset:20480
	ds_read_b128 v[156:159], v164 offset:22528
	ds_read_b128 v[108:111], v165
	ds_read_b128 v[112:115], v165 offset:2048
	ds_read_b128 v[116:119], v165 offset:4096
	ds_read_b128 v[120:123], v165 offset:6144
	ds_read_b128 v[124:127], v165 offset:8192
	ds_read_b128 v[132:135], v165 offset:10240
	ds_read_b128 v[136:139], v165 offset:12288
	ds_read_b128 v[140:143], v165 offset:14336
	ds_read_b128 v[144:147], v165 offset:16384
	ds_read_b128 v[148:151], v165 offset:18432
	s_waitcnt lgkmcnt(9)
	v_mfma_f32_16x16x32_bf16 v[76:79], v[152:155], v[108:111], v[76:79]
	v_mfma_f32_16x16x32_bf16 v[72:75], v[156:159], v[108:111], v[72:75]
	ds_read_b128 v[200:203], v192 offset:20480
	s_waitcnt lgkmcnt(9)
	v_mfma_f32_16x16x32_bf16 v[68:71], v[152:155], v[112:115], v[68:71]
	v_mfma_f32_16x16x32_bf16 v[64:67], v[156:159], v[112:115], v[64:67]
	ds_read_b128 v[204:207], v192 offset:22528
	s_waitcnt lgkmcnt(9)
	v_mfma_f32_16x16x32_bf16 v[60:63], v[152:155], v[116:119], v[60:63]
	v_mfma_f32_16x16x32_bf16 v[56:59], v[156:159], v[116:119], v[56:59]
	ds_read_b128 v[160:163], v196
	s_waitcnt lgkmcnt(9)
	v_mfma_f32_16x16x32_bf16 v[52:55], v[152:155], v[120:123], v[52:55]
	v_mfma_f32_16x16x32_bf16 v[48:51], v[156:159], v[120:123], v[48:51]
	ds_read_b128 v[164:167], v196 offset:2048
	s_waitcnt lgkmcnt(9)
	v_mfma_f32_16x16x32_bf16 v[44:47], v[152:155], v[124:127], v[44:47]
	v_mfma_f32_16x16x32_bf16 v[40:43], v[156:159], v[124:127], v[40:43]
	ds_read_b128 v[168:171], v196 offset:4096
	s_waitcnt lgkmcnt(9)
	v_mfma_f32_16x16x32_bf16 v[36:39], v[152:155], v[132:135], v[36:39]
	v_mfma_f32_16x16x32_bf16 v[32:35], v[156:159], v[132:135], v[32:35]
	ds_read_b128 v[172:175], v196 offset:6144
	s_waitcnt lgkmcnt(9)
	v_mfma_f32_16x16x32_bf16 v[28:31], v[152:155], v[136:139], v[28:31]
	v_mfma_f32_16x16x32_bf16 v[24:27], v[156:159], v[136:139], v[24:27]
	ds_read_b128 v[176:179], v196 offset:8192
	s_waitcnt lgkmcnt(9)
	v_mfma_f32_16x16x32_bf16 v[20:23], v[152:155], v[140:143], v[20:23]
	v_mfma_f32_16x16x32_bf16 v[16:19], v[156:159], v[140:143], v[16:19]
	ds_read_b128 v[180:183], v196 offset:10240
	s_waitcnt lgkmcnt(9)
	v_mfma_f32_16x16x32_bf16 v[12:15], v[152:155], v[144:147], v[12:15]
	v_mfma_f32_16x16x32_bf16 v[8:11], v[156:159], v[144:147], v[8:11]
	ds_read_b128 v[184:187], v196 offset:12288
	s_waitcnt lgkmcnt(9)
	v_mfma_f32_16x16x32_bf16 v[4:7], v[152:155], v[148:151], v[4:7]
	v_mfma_f32_16x16x32_bf16 v[0:3], v[156:159], v[148:151], v[0:3]
	ds_read_b128 v[188:191], v196 offset:14336
	ds_read_b128 v[192:195], v196 offset:16384
	ds_read_b128 v[196:199], v196 offset:18432
	s_waitcnt lgkmcnt(9)
	v_mfma_f32_16x16x32_bf16 v[76:79], v[200:203], v[160:163], v[76:79]
	v_mfma_f32_16x16x32_bf16 v[72:75], v[204:207], v[160:163], v[72:75]
	s_waitcnt lgkmcnt(8)
	v_mfma_f32_16x16x32_bf16 v[68:71], v[200:203], v[164:167], v[68:71]
	v_mfma_f32_16x16x32_bf16 v[64:67], v[204:207], v[164:167], v[64:67]
	s_waitcnt lgkmcnt(7)
	v_mfma_f32_16x16x32_bf16 v[60:63], v[200:203], v[168:171], v[60:63]
	v_mfma_f32_16x16x32_bf16 v[56:59], v[204:207], v[168:171], v[56:59]
	s_waitcnt lgkmcnt(6)
	v_mfma_f32_16x16x32_bf16 v[52:55], v[200:203], v[172:175], v[52:55]
	v_mfma_f32_16x16x32_bf16 v[48:51], v[204:207], v[172:175], v[48:51]
	s_waitcnt lgkmcnt(5)
	v_mfma_f32_16x16x32_bf16 v[44:47], v[200:203], v[176:179], v[44:47]
	v_mfma_f32_16x16x32_bf16 v[40:43], v[204:207], v[176:179], v[40:43]
	s_waitcnt lgkmcnt(4)
	v_mfma_f32_16x16x32_bf16 v[36:39], v[200:203], v[180:183], v[36:39]
	v_mfma_f32_16x16x32_bf16 v[32:35], v[204:207], v[180:183], v[32:35]
	s_waitcnt lgkmcnt(3)
	v_mfma_f32_16x16x32_bf16 v[28:31], v[200:203], v[184:187], v[28:31]
	v_mfma_f32_16x16x32_bf16 v[24:27], v[204:207], v[184:187], v[24:27]
	s_waitcnt lgkmcnt(2)
	v_mfma_f32_16x16x32_bf16 v[20:23], v[200:203], v[188:191], v[20:23]
	v_mfma_f32_16x16x32_bf16 v[16:19], v[204:207], v[188:191], v[16:19]
	s_waitcnt lgkmcnt(1)
	v_mfma_f32_16x16x32_bf16 v[12:15], v[200:203], v[192:195], v[12:15]
	v_mfma_f32_16x16x32_bf16 v[8:11], v[204:207], v[192:195], v[8:11]
	s_waitcnt lgkmcnt(0)
	v_mfma_f32_16x16x32_bf16 v[4:7], v[200:203], v[196:199], v[4:7]
	v_mfma_f32_16x16x32_bf16 v[0:3], v[204:207], v[196:199], v[0:3]
	s_add_u32 s9, s9, 0xd000
	s_cmp_eq_u32 s9, 0x27000
	s_cselect_b32 s9, 0, s9
	s_branch .Lg160d_epi
